# MLP-up epilogue: the 8 per-block ssq-partial loads hoisted to the epilogue head with counted waits (blocks no longer wait for the previous block's stores)
# speedup vs baseline: 1.0660x; 1.0019x over previous
.LBB0_702:
	v_lshl_add_u32 v146, s6, 8, v148
	v_ashrrev_i32_e32 v147, 31, v146
	v_lshlrev_b64 v[144:145], 6, v[146:147]
	v_lshl_add_u64 v[144:145], s[10:11], 0, v[144:145]
	v_bfe_u32 v164, v206, 4, 2
	v_lshlrev_b32_e32 v164, 4, v164
	v_mov_b32_e32 v165, 0
	v_lshl_add_u64 v[160:161], v[144:145], 0, v[164:165]
	global_load_dwordx4 v[184:187], v[160:161], off
	global_load_dwordx4 v[188:191], v[160:161], off offset:1024
	global_load_dwordx4 v[192:195], v[160:161], off offset:2048
	global_load_dwordx4 v[196:199], v[160:161], off offset:3072
	s_mov_b64 s[100:101], 0x2000
	v_lshl_add_u64 v[220:221], v[160:161], 0, s[100:101]
	global_load_dwordx4 v[200:203], v[220:221], off
	global_load_dwordx4 v[208:211], v[220:221], off offset:1024
	global_load_dwordx4 v[212:215], v[220:221], off offset:2048
	global_load_dwordx4 v[216:219], v[220:221], off offset:3072
	v_lshlrev_b64 v[174:175], 13, v[146:147]
	v_lshl_or_b32 v144, s7, 8, v150
	v_ashrrev_i32_e32 v145, 31, v144
	v_or_b32_e32 v172, 16, v146
	v_lshl_add_u64 v[144:145], v[144:145], 1, s[12:13]
	v_ashrrev_i32_e32 v173, 31, v172
	s_waitcnt vmcnt(7)
	v_add_f32_e32 v160, v184, v185
	v_add_f32_e32 v161, v186, v187
	v_add_f32_e32 v160, v160, v161
	ds_swizzle_b32 v161, v160 offset:swizzle(SWAP,16)
	s_waitcnt lgkmcnt(0)
	v_add_f32_e32 v160, v160, v161
	v_mov_b32_e32 v161, v160
	s_nop 1
	v_permlane32_swap_b32_e32 v160, v161
	v_add_f32_e32 v168, v160, v161
	s_nop 0
	v_lshlrev_b64 v[158:159], 6, v[172:173]
	v_mov_b32_e32 v147, v168
	v_fmamk_f32 v147, v147, 0x3a800000, v154
	v_mul_f32_e32 v155, 0x4b800000, v147
	v_cmp_gt_f32_e32 vcc, s48, v147
	v_lshl_add_u64 v[156:157], v[144:145], 0, v[174:175]
	v_lshl_add_u64 v[158:159], s[10:11], 0, v[158:159]
	v_cndmask_b32_e32 v147, v147, v155, vcc
	v_rsq_f32_e32 v147, v147
	s_nop 0
	v_mul_f32_e32 v155, 0x45800000, v147
	v_cndmask_b32_e32 v160, v147, v155, vcc
	v_pk_mul_f32 v[126:127], v[126:127], v[160:161] op_sel_hi:[1,0]
	v_pk_mul_f32 v[124:125], v[124:125], v[160:161] op_sel_hi:[1,0]
	v_pk_mul_f32 v[122:123], v[122:123], v[160:161] op_sel_hi:[1,0]
	v_pk_mul_f32 v[120:121], v[120:121], v[160:161] op_sel_hi:[1,0]
	v_pk_mul_f32 v[114:115], v[114:115], v[160:161] op_sel_hi:[1,0]
	v_pk_mul_f32 v[112:113], v[112:113], v[160:161] op_sel_hi:[1,0]
	v_pk_mul_f32 v[118:119], v[118:119], v[160:161] op_sel_hi:[1,0]
	v_pk_mul_f32 v[116:117], v[116:117], v[160:161] op_sel_hi:[1,0]
	v_max_f32_e32 v124, 0, v124
	v_max_f32_e32 v120, 0, v120
	v_max_f32_e32 v125, 0, v125
	v_max_f32_e32 v121, 0, v121
	v_max_f32_e32 v126, 0, v126
	v_max_f32_e32 v122, 0, v122
	v_max_f32_e32 v127, 0, v127
	v_max_f32_e32 v123, 0, v123
	v_max_f32_e32 v112, 0, v112
	v_max_f32_e32 v113, 0, v113
	v_max_f32_e32 v114, 0, v114
	v_max_f32_e32 v115, 0, v115
	v_max_f32_e32 v116, 0, v116
	v_max_f32_e32 v117, 0, v117
	v_max_f32_e32 v118, 0, v118
	v_max_f32_e32 v119, 0, v119
	v_mul_f32_e32 v124, v124, v124
	v_mul_f32_e32 v120, v120, v120
	v_mul_f32_e32 v125, v125, v125
	v_mul_f32_e32 v121, v121, v121
	v_mul_f32_e32 v126, v126, v126
	v_mul_f32_e32 v122, v122, v122
	v_mul_f32_e32 v127, v127, v127
	v_mul_f32_e32 v123, v123, v123
	v_mul_f32_e32 v147, v112, v112
	v_mul_f32_e32 v155, v113, v113
	v_mul_f32_e32 v160, v114, v114
	v_mul_f32_e32 v161, v115, v115
	v_cvt_pk_bf16_f32 v112, v124, v125
	v_cvt_pk_bf16_f32 v113, v126, v127
	v_cvt_pk_bf16_f32 v114, v120, v121
	v_cvt_pk_bf16_f32 v115, v122, v123
	v_mul_f32_e32 v116, v116, v116
	v_mul_f32_e32 v117, v117, v117
	v_mul_f32_e32 v118, v118, v118
	v_mul_f32_e32 v119, v119, v119
	global_store_dwordx4 v[156:157], v[112:115], off
	s_nop 1
	v_cvt_pk_bf16_f32 v112, v116, v117
	v_cvt_pk_bf16_f32 v113, v118, v119
	v_cvt_pk_bf16_f32 v114, v147, v155
	v_cvt_pk_bf16_f32 v115, v160, v161
	global_store_dwordx4 v[156:157], v[112:115], off offset:256
	s_nop 0
	v_or_b32_e32 v156, 32, v146
	v_ashrrev_i32_e32 v157, 31, v156
	v_lshlrev_b64 v[158:159], 13, v[172:173]
	s_waitcnt vmcnt(8)
	v_add_f32_e32 v116, v188, v189
	v_add_f32_e32 v117, v190, v191
	v_add_f32_e32 v116, v116, v117
	ds_swizzle_b32 v117, v116 offset:swizzle(SWAP,16)
	s_waitcnt lgkmcnt(0)
	v_add_f32_e32 v116, v116, v117
	v_mov_b32_e32 v117, v116
	s_nop 1
	v_permlane32_swap_b32_e32 v116, v117
	v_add_f32_e32 v124, v116, v117
	s_nop 0
	v_lshl_add_u64 v[114:115], v[144:145], 0, v[158:159]
	v_mov_b32_e32 v112, v124
	v_fmamk_f32 v112, v112, 0x3a800000, v154
	v_mul_f32_e32 v113, 0x4b800000, v112
	v_cmp_gt_f32_e32 vcc, s48, v112
	s_nop 1
	v_cndmask_b32_e32 v112, v112, v113, vcc
	v_rsq_f32_e32 v116, v112
	v_lshlrev_b64 v[112:113], 6, v[156:157]
	v_lshl_add_u64 v[112:113], s[10:11], 0, v[112:113]
	v_mul_f32_e32 v117, 0x45800000, v116
	v_cndmask_b32_e32 v116, v116, v117, vcc
	v_pk_mul_f32 v[110:111], v[110:111], v[116:117] op_sel_hi:[1,0]
	v_pk_mul_f32 v[108:109], v[108:109], v[116:117] op_sel_hi:[1,0]
	v_pk_mul_f32 v[106:107], v[106:107], v[116:117] op_sel_hi:[1,0]
	v_pk_mul_f32 v[104:105], v[104:105], v[116:117] op_sel_hi:[1,0]
	v_pk_mul_f32 v[98:99], v[98:99], v[116:117] op_sel_hi:[1,0]
	v_pk_mul_f32 v[96:97], v[96:97], v[116:117] op_sel_hi:[1,0]
	v_pk_mul_f32 v[102:103], v[102:103], v[116:117] op_sel_hi:[1,0]
	v_pk_mul_f32 v[100:101], v[100:101], v[116:117] op_sel_hi:[1,0]
	v_max_f32_e32 v108, 0, v108
	v_max_f32_e32 v104, 0, v104
	v_max_f32_e32 v109, 0, v109
	v_max_f32_e32 v105, 0, v105
	v_max_f32_e32 v110, 0, v110
	v_max_f32_e32 v106, 0, v106
	v_max_f32_e32 v111, 0, v111
	v_max_f32_e32 v107, 0, v107
	v_max_f32_e32 v96, 0, v96
	v_max_f32_e32 v97, 0, v97
	v_max_f32_e32 v98, 0, v98
	v_max_f32_e32 v99, 0, v99
	v_max_f32_e32 v100, 0, v100
	v_max_f32_e32 v101, 0, v101
	v_max_f32_e32 v102, 0, v102
	v_max_f32_e32 v103, 0, v103
	v_mul_f32_e32 v108, v108, v108
	v_mul_f32_e32 v104, v104, v104
	v_mul_f32_e32 v109, v109, v109
	v_mul_f32_e32 v105, v105, v105
	v_mul_f32_e32 v110, v110, v110
	v_mul_f32_e32 v106, v106, v106
	v_mul_f32_e32 v111, v111, v111
	v_mul_f32_e32 v107, v107, v107
	v_mul_f32_e32 v116, v96, v96
	v_mul_f32_e32 v117, v97, v97
	v_mul_f32_e32 v118, v98, v98
	v_mul_f32_e32 v119, v99, v99
	v_cvt_pk_bf16_f32 v96, v108, v109
	v_cvt_pk_bf16_f32 v97, v110, v111
	v_cvt_pk_bf16_f32 v98, v104, v105
	v_cvt_pk_bf16_f32 v99, v106, v107
	v_mul_f32_e32 v100, v100, v100
	v_mul_f32_e32 v101, v101, v101
	v_mul_f32_e32 v102, v102, v102
	v_mul_f32_e32 v103, v103, v103
	global_store_dwordx4 v[114:115], v[96:99], off
	s_nop 1
	v_cvt_pk_bf16_f32 v96, v100, v101
	v_cvt_pk_bf16_f32 v97, v102, v103
	v_cvt_pk_bf16_f32 v98, v116, v117
	v_cvt_pk_bf16_f32 v99, v118, v119
	global_store_dwordx4 v[114:115], v[96:99], off offset:256
	s_nop 0
	v_or_b32_e32 v112, 48, v146
	v_ashrrev_i32_e32 v113, 31, v112
	v_lshlrev_b64 v[114:115], 13, v[156:157]
	s_waitcnt vmcnt(9)
	v_add_f32_e32 v100, v192, v193
	v_add_f32_e32 v101, v194, v195
	v_add_f32_e32 v100, v100, v101
	ds_swizzle_b32 v101, v100 offset:swizzle(SWAP,16)
	s_waitcnt lgkmcnt(0)
	v_add_f32_e32 v100, v100, v101
	v_mov_b32_e32 v101, v100
	s_nop 1
	v_permlane32_swap_b32_e32 v100, v101
	v_add_f32_e32 v108, v100, v101
	s_nop 0
	v_lshl_add_u64 v[98:99], v[144:145], 0, v[114:115]
	v_mov_b32_e32 v96, v108
	v_fmamk_f32 v96, v96, 0x3a800000, v154
	v_mul_f32_e32 v97, 0x4b800000, v96
	v_cmp_gt_f32_e32 vcc, s48, v96
	s_nop 1
	v_cndmask_b32_e32 v96, v96, v97, vcc
	v_rsq_f32_e32 v100, v96
	v_lshlrev_b64 v[96:97], 6, v[112:113]
	v_lshl_add_u64 v[96:97], s[10:11], 0, v[96:97]
	v_mul_f32_e32 v101, 0x45800000, v100
	v_cndmask_b32_e32 v100, v100, v101, vcc
	v_pk_mul_f32 v[94:95], v[94:95], v[100:101] op_sel_hi:[1,0]
	v_pk_mul_f32 v[92:93], v[92:93], v[100:101] op_sel_hi:[1,0]
	v_pk_mul_f32 v[90:91], v[90:91], v[100:101] op_sel_hi:[1,0]
	v_pk_mul_f32 v[88:89], v[88:89], v[100:101] op_sel_hi:[1,0]
	v_pk_mul_f32 v[82:83], v[82:83], v[100:101] op_sel_hi:[1,0]
	v_pk_mul_f32 v[80:81], v[80:81], v[100:101] op_sel_hi:[1,0]
	v_pk_mul_f32 v[86:87], v[86:87], v[100:101] op_sel_hi:[1,0]
	v_pk_mul_f32 v[84:85], v[84:85], v[100:101] op_sel_hi:[1,0]
	v_max_f32_e32 v92, 0, v92
	v_max_f32_e32 v88, 0, v88
	v_max_f32_e32 v93, 0, v93
	v_max_f32_e32 v89, 0, v89
	v_max_f32_e32 v94, 0, v94
	v_max_f32_e32 v90, 0, v90
	v_max_f32_e32 v95, 0, v95
	v_max_f32_e32 v91, 0, v91
	v_max_f32_e32 v80, 0, v80
	v_max_f32_e32 v81, 0, v81
	v_max_f32_e32 v82, 0, v82
	v_max_f32_e32 v83, 0, v83
	v_max_f32_e32 v84, 0, v84
	v_max_f32_e32 v85, 0, v85
	v_max_f32_e32 v86, 0, v86
	v_max_f32_e32 v87, 0, v87
	v_mul_f32_e32 v92, v92, v92
	v_mul_f32_e32 v88, v88, v88
	v_mul_f32_e32 v93, v93, v93
	v_mul_f32_e32 v89, v89, v89
	v_mul_f32_e32 v94, v94, v94
	v_mul_f32_e32 v90, v90, v90
	v_mul_f32_e32 v95, v95, v95
	v_mul_f32_e32 v91, v91, v91
	v_mul_f32_e32 v100, v80, v80
	v_mul_f32_e32 v101, v81, v81
	v_mul_f32_e32 v102, v82, v82
	v_mul_f32_e32 v103, v83, v83
	v_cvt_pk_bf16_f32 v80, v92, v93
	v_cvt_pk_bf16_f32 v81, v94, v95
	v_cvt_pk_bf16_f32 v82, v88, v89
	v_cvt_pk_bf16_f32 v83, v90, v91
	v_mul_f32_e32 v84, v84, v84
	v_mul_f32_e32 v85, v85, v85
	v_mul_f32_e32 v86, v86, v86
	v_mul_f32_e32 v87, v87, v87
	global_store_dwordx4 v[98:99], v[80:83], off
	s_nop 1
	v_cvt_pk_bf16_f32 v80, v84, v85
	v_cvt_pk_bf16_f32 v81, v86, v87
	v_cvt_pk_bf16_f32 v82, v100, v101
	v_cvt_pk_bf16_f32 v83, v102, v103
	global_store_dwordx4 v[98:99], v[80:83], off offset:256
	s_nop 0
	v_add_u32_e32 v96, 0x80, v146
	v_ashrrev_i32_e32 v97, 31, v96
	v_lshlrev_b64 v[98:99], 13, v[112:113]
	s_waitcnt vmcnt(10)
	v_add_f32_e32 v84, v196, v197
	v_add_f32_e32 v85, v198, v199
	v_add_f32_e32 v84, v84, v85
	ds_swizzle_b32 v85, v84 offset:swizzle(SWAP,16)
	s_waitcnt lgkmcnt(0)
	v_add_f32_e32 v84, v84, v85
	v_mov_b32_e32 v85, v84
	s_nop 1
	v_permlane32_swap_b32_e32 v84, v85
	v_add_f32_e32 v92, v84, v85
	s_nop 0
	v_lshl_add_u64 v[82:83], v[144:145], 0, v[98:99]
	v_mov_b32_e32 v80, v92
	v_fmamk_f32 v80, v80, 0x3a800000, v154
	v_mul_f32_e32 v81, 0x4b800000, v80
	v_cmp_gt_f32_e32 vcc, s48, v80
	s_nop 1
	v_cndmask_b32_e32 v80, v80, v81, vcc
	v_rsq_f32_e32 v84, v80
	v_lshlrev_b64 v[80:81], 6, v[96:97]
	v_lshl_add_u64 v[80:81], s[10:11], 0, v[80:81]
	v_mul_f32_e32 v85, 0x45800000, v84
	v_cndmask_b32_e32 v84, v84, v85, vcc
	v_pk_mul_f32 v[78:79], v[78:79], v[84:85] op_sel_hi:[1,0]
	v_pk_mul_f32 v[76:77], v[76:77], v[84:85] op_sel_hi:[1,0]
	v_pk_mul_f32 v[74:75], v[74:75], v[84:85] op_sel_hi:[1,0]
	v_pk_mul_f32 v[72:73], v[72:73], v[84:85] op_sel_hi:[1,0]
	v_pk_mul_f32 v[66:67], v[66:67], v[84:85] op_sel_hi:[1,0]
	v_pk_mul_f32 v[64:65], v[64:65], v[84:85] op_sel_hi:[1,0]
	v_pk_mul_f32 v[70:71], v[70:71], v[84:85] op_sel_hi:[1,0]
	v_pk_mul_f32 v[68:69], v[68:69], v[84:85] op_sel_hi:[1,0]
	v_max_f32_e32 v76, 0, v76
	v_max_f32_e32 v72, 0, v72
	v_max_f32_e32 v77, 0, v77
	v_max_f32_e32 v73, 0, v73
	v_max_f32_e32 v78, 0, v78
	v_max_f32_e32 v74, 0, v74
	v_max_f32_e32 v79, 0, v79
	v_max_f32_e32 v75, 0, v75
	v_max_f32_e32 v64, 0, v64
	v_max_f32_e32 v65, 0, v65
	v_max_f32_e32 v66, 0, v66
	v_max_f32_e32 v67, 0, v67
	v_max_f32_e32 v68, 0, v68
	v_max_f32_e32 v69, 0, v69
	v_max_f32_e32 v70, 0, v70
	v_max_f32_e32 v71, 0, v71
	v_mul_f32_e32 v76, v76, v76
	v_mul_f32_e32 v72, v72, v72
	v_mul_f32_e32 v77, v77, v77
	v_mul_f32_e32 v73, v73, v73
	v_mul_f32_e32 v78, v78, v78
	v_mul_f32_e32 v74, v74, v74
	v_mul_f32_e32 v79, v79, v79
	v_mul_f32_e32 v75, v75, v75
	v_mul_f32_e32 v84, v64, v64
	v_mul_f32_e32 v85, v65, v65
	v_mul_f32_e32 v86, v66, v66
	v_mul_f32_e32 v87, v67, v67
	v_cvt_pk_bf16_f32 v64, v76, v77
	v_cvt_pk_bf16_f32 v65, v78, v79
	v_cvt_pk_bf16_f32 v66, v72, v73
	v_cvt_pk_bf16_f32 v67, v74, v75
	v_mul_f32_e32 v68, v68, v68
	v_mul_f32_e32 v69, v69, v69
	v_mul_f32_e32 v70, v70, v70
	v_mul_f32_e32 v71, v71, v71
	global_store_dwordx4 v[82:83], v[64:67], off
	s_nop 1
	v_cvt_pk_bf16_f32 v64, v68, v69
	v_cvt_pk_bf16_f32 v65, v70, v71
	v_cvt_pk_bf16_f32 v66, v84, v85
	v_cvt_pk_bf16_f32 v67, v86, v87
	global_store_dwordx4 v[82:83], v[64:67], off offset:256
	s_nop 0
	v_add_u32_e32 v80, 0x90, v146
	v_ashrrev_i32_e32 v81, 31, v80
	v_lshlrev_b64 v[82:83], 13, v[96:97]
	s_waitcnt vmcnt(11)
	v_add_f32_e32 v68, v200, v201
	v_add_f32_e32 v69, v202, v203
	v_add_f32_e32 v68, v68, v69
	ds_swizzle_b32 v69, v68 offset:swizzle(SWAP,16)
	s_waitcnt lgkmcnt(0)
	v_add_f32_e32 v68, v68, v69
	v_mov_b32_e32 v69, v68
	s_nop 1
	v_permlane32_swap_b32_e32 v68, v69
	v_add_f32_e32 v76, v68, v69
	s_nop 0
	v_lshl_add_u64 v[66:67], v[144:145], 0, v[82:83]
	v_mov_b32_e32 v64, v76
	v_fmamk_f32 v64, v64, 0x3a800000, v154
	v_mul_f32_e32 v65, 0x4b800000, v64
	v_cmp_gt_f32_e32 vcc, s48, v64
	s_nop 1
	v_cndmask_b32_e32 v64, v64, v65, vcc
	v_rsq_f32_e32 v68, v64
	v_lshlrev_b64 v[64:65], 6, v[80:81]
	v_lshl_add_u64 v[64:65], s[10:11], 0, v[64:65]
	v_mul_f32_e32 v69, 0x45800000, v68
	v_cndmask_b32_e32 v68, v68, v69, vcc
	v_pk_mul_f32 v[62:63], v[62:63], v[68:69] op_sel_hi:[1,0]
	v_pk_mul_f32 v[60:61], v[60:61], v[68:69] op_sel_hi:[1,0]
	v_pk_mul_f32 v[58:59], v[58:59], v[68:69] op_sel_hi:[1,0]
	v_pk_mul_f32 v[56:57], v[56:57], v[68:69] op_sel_hi:[1,0]
	v_pk_mul_f32 v[50:51], v[50:51], v[68:69] op_sel_hi:[1,0]
	v_pk_mul_f32 v[48:49], v[48:49], v[68:69] op_sel_hi:[1,0]
	v_pk_mul_f32 v[54:55], v[54:55], v[68:69] op_sel_hi:[1,0]
	v_pk_mul_f32 v[52:53], v[52:53], v[68:69] op_sel_hi:[1,0]
	v_max_f32_e32 v60, 0, v60
	v_max_f32_e32 v56, 0, v56
	v_max_f32_e32 v61, 0, v61
	v_max_f32_e32 v57, 0, v57
	v_max_f32_e32 v62, 0, v62
	v_max_f32_e32 v58, 0, v58
	v_max_f32_e32 v63, 0, v63
	v_max_f32_e32 v59, 0, v59
	v_max_f32_e32 v48, 0, v48
	v_max_f32_e32 v49, 0, v49
	v_max_f32_e32 v50, 0, v50
	v_max_f32_e32 v51, 0, v51
	v_max_f32_e32 v52, 0, v52
	v_max_f32_e32 v53, 0, v53
	v_max_f32_e32 v54, 0, v54
	v_max_f32_e32 v55, 0, v55
	v_mul_f32_e32 v60, v60, v60
	v_mul_f32_e32 v56, v56, v56
	v_mul_f32_e32 v61, v61, v61
	v_mul_f32_e32 v57, v57, v57
	v_mul_f32_e32 v62, v62, v62
	v_mul_f32_e32 v58, v58, v58
	v_mul_f32_e32 v63, v63, v63
	v_mul_f32_e32 v59, v59, v59
	v_mul_f32_e32 v68, v48, v48
	v_mul_f32_e32 v69, v49, v49
	v_mul_f32_e32 v70, v50, v50
	v_mul_f32_e32 v71, v51, v51
	v_cvt_pk_bf16_f32 v48, v60, v61
	v_cvt_pk_bf16_f32 v49, v62, v63
	v_cvt_pk_bf16_f32 v50, v56, v57
	v_cvt_pk_bf16_f32 v51, v58, v59
	v_mul_f32_e32 v52, v52, v52
	v_mul_f32_e32 v53, v53, v53
	v_mul_f32_e32 v54, v54, v54
	v_mul_f32_e32 v55, v55, v55
	global_store_dwordx4 v[66:67], v[48:51], off
	s_nop 1
	v_cvt_pk_bf16_f32 v48, v52, v53
	v_cvt_pk_bf16_f32 v49, v54, v55
	v_cvt_pk_bf16_f32 v50, v68, v69
	v_cvt_pk_bf16_f32 v51, v70, v71
	global_store_dwordx4 v[66:67], v[48:51], off offset:256
	s_nop 0
	v_add_u32_e32 v64, 0xa0, v146
	v_ashrrev_i32_e32 v65, 31, v64
	v_lshlrev_b64 v[66:67], 13, v[80:81]
	s_waitcnt vmcnt(12)
	v_add_f32_e32 v52, v208, v209
	v_add_f32_e32 v53, v210, v211
	v_add_f32_e32 v52, v52, v53
	ds_swizzle_b32 v53, v52 offset:swizzle(SWAP,16)
	s_waitcnt lgkmcnt(0)
	v_add_f32_e32 v52, v52, v53
	v_mov_b32_e32 v53, v52
	s_nop 1
	v_permlane32_swap_b32_e32 v52, v53
	v_add_f32_e32 v60, v52, v53
	s_nop 0
	v_lshl_add_u64 v[50:51], v[144:145], 0, v[66:67]
	v_mov_b32_e32 v48, v60
	v_fmamk_f32 v48, v48, 0x3a800000, v154
	v_mul_f32_e32 v49, 0x4b800000, v48
	v_cmp_gt_f32_e32 vcc, s48, v48
	s_nop 1
	v_cndmask_b32_e32 v48, v48, v49, vcc
	v_rsq_f32_e32 v52, v48
	v_lshlrev_b64 v[48:49], 6, v[64:65]
	v_lshl_add_u64 v[48:49], s[10:11], 0, v[48:49]
	v_mul_f32_e32 v53, 0x45800000, v52
	v_cndmask_b32_e32 v52, v52, v53, vcc
	v_pk_mul_f32 v[46:47], v[46:47], v[52:53] op_sel_hi:[1,0]
	v_pk_mul_f32 v[44:45], v[44:45], v[52:53] op_sel_hi:[1,0]
	v_pk_mul_f32 v[42:43], v[42:43], v[52:53] op_sel_hi:[1,0]
	v_pk_mul_f32 v[40:41], v[40:41], v[52:53] op_sel_hi:[1,0]
	v_pk_mul_f32 v[34:35], v[34:35], v[52:53] op_sel_hi:[1,0]
	v_pk_mul_f32 v[32:33], v[32:33], v[52:53] op_sel_hi:[1,0]
	v_pk_mul_f32 v[38:39], v[38:39], v[52:53] op_sel_hi:[1,0]
	v_pk_mul_f32 v[36:37], v[36:37], v[52:53] op_sel_hi:[1,0]
	v_max_f32_e32 v44, 0, v44
	v_max_f32_e32 v40, 0, v40
	v_max_f32_e32 v45, 0, v45
	v_max_f32_e32 v41, 0, v41
	v_max_f32_e32 v46, 0, v46
	v_max_f32_e32 v42, 0, v42
	v_max_f32_e32 v47, 0, v47
	v_max_f32_e32 v43, 0, v43
	v_max_f32_e32 v32, 0, v32
	v_max_f32_e32 v33, 0, v33
	v_max_f32_e32 v34, 0, v34
	v_max_f32_e32 v35, 0, v35
	v_max_f32_e32 v36, 0, v36
	v_max_f32_e32 v37, 0, v37
	v_max_f32_e32 v38, 0, v38
	v_max_f32_e32 v39, 0, v39
	v_mul_f32_e32 v44, v44, v44
	v_mul_f32_e32 v40, v40, v40
	v_mul_f32_e32 v45, v45, v45
	v_mul_f32_e32 v41, v41, v41
	v_mul_f32_e32 v46, v46, v46
	v_mul_f32_e32 v42, v42, v42
	v_mul_f32_e32 v47, v47, v47
	v_mul_f32_e32 v43, v43, v43
	v_mul_f32_e32 v52, v32, v32
	v_mul_f32_e32 v53, v33, v33
	v_mul_f32_e32 v54, v34, v34
	v_mul_f32_e32 v55, v35, v35
	v_cvt_pk_bf16_f32 v32, v44, v45
	v_cvt_pk_bf16_f32 v33, v46, v47
	v_cvt_pk_bf16_f32 v34, v40, v41
	v_cvt_pk_bf16_f32 v35, v42, v43
	v_mul_f32_e32 v36, v36, v36
	v_mul_f32_e32 v37, v37, v37
	v_mul_f32_e32 v38, v38, v38
	v_mul_f32_e32 v39, v39, v39
	global_store_dwordx4 v[50:51], v[32:35], off
	s_nop 1
	v_cvt_pk_bf16_f32 v32, v36, v37
	v_cvt_pk_bf16_f32 v33, v38, v39
	v_cvt_pk_bf16_f32 v34, v52, v53
	v_cvt_pk_bf16_f32 v35, v54, v55
	global_store_dwordx4 v[50:51], v[32:35], off offset:256
	s_nop 0
	v_add_u32_e32 v48, 0xb0, v146
	v_ashrrev_i32_e32 v49, 31, v48
	v_lshlrev_b64 v[50:51], 13, v[64:65]
	s_waitcnt vmcnt(13)
	v_add_f32_e32 v36, v212, v213
	v_add_f32_e32 v37, v214, v215
	v_add_f32_e32 v36, v36, v37
	ds_swizzle_b32 v37, v36 offset:swizzle(SWAP,16)
	s_waitcnt lgkmcnt(0)
	v_add_f32_e32 v36, v36, v37
	v_mov_b32_e32 v37, v36
	s_nop 1
	v_permlane32_swap_b32_e32 v36, v37
	v_add_f32_e32 v44, v36, v37
	s_nop 0
	v_lshl_add_u64 v[34:35], v[144:145], 0, v[50:51]
	v_mov_b32_e32 v32, v44
	v_fmamk_f32 v32, v32, 0x3a800000, v154
	v_mul_f32_e32 v33, 0x4b800000, v32
	v_cmp_gt_f32_e32 vcc, s48, v32
	s_nop 1
	v_cndmask_b32_e32 v32, v32, v33, vcc
	v_rsq_f32_e32 v36, v32
	v_lshlrev_b64 v[32:33], 6, v[48:49]
	v_lshl_add_u64 v[32:33], s[10:11], 0, v[32:33]
	v_mul_f32_e32 v37, 0x45800000, v36
	v_cndmask_b32_e32 v36, v36, v37, vcc
	v_pk_mul_f32 v[30:31], v[30:31], v[36:37] op_sel_hi:[1,0]
	v_pk_mul_f32 v[28:29], v[28:29], v[36:37] op_sel_hi:[1,0]
	v_pk_mul_f32 v[26:27], v[26:27], v[36:37] op_sel_hi:[1,0]
	v_pk_mul_f32 v[24:25], v[24:25], v[36:37] op_sel_hi:[1,0]
	v_pk_mul_f32 v[18:19], v[18:19], v[36:37] op_sel_hi:[1,0]
	v_pk_mul_f32 v[16:17], v[16:17], v[36:37] op_sel_hi:[1,0]
	v_pk_mul_f32 v[22:23], v[22:23], v[36:37] op_sel_hi:[1,0]
	v_pk_mul_f32 v[20:21], v[20:21], v[36:37] op_sel_hi:[1,0]
	v_max_f32_e32 v28, 0, v28
	v_max_f32_e32 v24, 0, v24
	v_max_f32_e32 v29, 0, v29
	v_max_f32_e32 v25, 0, v25
	v_max_f32_e32 v30, 0, v30
	v_max_f32_e32 v26, 0, v26
	v_max_f32_e32 v31, 0, v31
	v_max_f32_e32 v27, 0, v27
	v_max_f32_e32 v16, 0, v16
	v_max_f32_e32 v17, 0, v17
	v_max_f32_e32 v18, 0, v18
	v_max_f32_e32 v19, 0, v19
	v_max_f32_e32 v20, 0, v20
	v_max_f32_e32 v21, 0, v21
	v_max_f32_e32 v22, 0, v22
	v_max_f32_e32 v23, 0, v23
	v_mul_f32_e32 v28, v28, v28
	v_mul_f32_e32 v24, v24, v24
	v_mul_f32_e32 v29, v29, v29
	v_mul_f32_e32 v25, v25, v25
	v_mul_f32_e32 v30, v30, v30
	v_mul_f32_e32 v26, v26, v26
	v_mul_f32_e32 v31, v31, v31
	v_mul_f32_e32 v27, v27, v27
	v_mul_f32_e32 v36, v16, v16
	v_mul_f32_e32 v37, v17, v17
	v_mul_f32_e32 v38, v18, v18
	v_mul_f32_e32 v39, v19, v19
	v_cvt_pk_bf16_f32 v16, v28, v29
	v_cvt_pk_bf16_f32 v17, v30, v31
	v_cvt_pk_bf16_f32 v18, v24, v25
	v_cvt_pk_bf16_f32 v19, v26, v27
	v_mul_f32_e32 v20, v20, v20
	v_mul_f32_e32 v21, v21, v21
	v_mul_f32_e32 v22, v22, v22
	v_mul_f32_e32 v23, v23, v23
	global_store_dwordx4 v[34:35], v[16:19], off
	s_andn2_b64 vcc, exec, s[4:5]
	s_mov_b64 s[4:5], -1
	v_cvt_pk_bf16_f32 v16, v20, v21
	v_cvt_pk_bf16_f32 v17, v22, v23
	v_cvt_pk_bf16_f32 v18, v36, v37
	v_cvt_pk_bf16_f32 v19, v38, v39
	global_store_dwordx4 v[34:35], v[16:19], off offset:256
	s_nop 0
	s_waitcnt vmcnt(14)
	v_add_f32_e32 v20, v216, v217
	v_add_f32_e32 v21, v218, v219
	v_add_f32_e32 v20, v20, v21
	ds_swizzle_b32 v21, v20 offset:swizzle(SWAP,16)
	s_waitcnt lgkmcnt(0)
	v_add_f32_e32 v20, v20, v21
	v_mov_b32_e32 v21, v20
	s_nop 1
	v_permlane32_swap_b32_e32 v20, v21
	v_add_f32_e32 v28, v20, v21
	s_nop 0
	s_nop 0
	v_mov_b32_e32 v16, v28
	v_fmamk_f32 v16, v16, 0x3a800000, v154
	v_mul_f32_e32 v17, 0x4b800000, v16
	v_cmp_gt_f32_e64 s[6:7], s48, v16
	s_nop 1
	v_cndmask_b32_e64 v16, v16, v17, s[6:7]
	v_rsq_f32_e32 v18, v16
	v_lshlrev_b64 v[16:17], 13, v[48:49]
	v_lshl_add_u64 v[16:17], v[144:145], 0, v[16:17]
	v_mul_f32_e32 v19, 0x45800000, v18
	v_cndmask_b32_e64 v18, v18, v19, s[6:7]
	v_pk_mul_f32 v[14:15], v[14:15], v[18:19] op_sel_hi:[1,0]
	v_pk_mul_f32 v[12:13], v[12:13], v[18:19] op_sel_hi:[1,0]
	v_pk_mul_f32 v[10:11], v[10:11], v[18:19] op_sel_hi:[1,0]
	v_pk_mul_f32 v[8:9], v[8:9], v[18:19] op_sel_hi:[1,0]
	v_pk_mul_f32 v[2:3], v[2:3], v[18:19] op_sel_hi:[1,0]
	v_pk_mul_f32 v[0:1], v[0:1], v[18:19] op_sel_hi:[1,0]
	v_pk_mul_f32 v[6:7], v[6:7], v[18:19] op_sel_hi:[1,0]
	v_pk_mul_f32 v[4:5], v[4:5], v[18:19] op_sel_hi:[1,0]
	v_max_f32_e32 v12, 0, v12
	v_max_f32_e32 v8, 0, v8
	v_max_f32_e32 v13, 0, v13
	v_max_f32_e32 v9, 0, v9
	v_max_f32_e32 v14, 0, v14
	v_max_f32_e32 v10, 0, v10
	v_max_f32_e32 v15, 0, v15
	v_max_f32_e32 v11, 0, v11
	v_max_f32_e32 v0, 0, v0
	v_max_f32_e32 v1, 0, v1
	v_max_f32_e32 v2, 0, v2
	v_max_f32_e32 v3, 0, v3
	v_max_f32_e32 v4, 0, v4
	v_max_f32_e32 v5, 0, v5
	v_max_f32_e32 v6, 0, v6
	v_max_f32_e32 v7, 0, v7
	v_mul_f32_e32 v12, v12, v12
	v_mul_f32_e32 v8, v8, v8
	v_mul_f32_e32 v13, v13, v13
	v_mul_f32_e32 v9, v9, v9
	v_mul_f32_e32 v14, v14, v14
	v_mul_f32_e32 v10, v10, v10
	v_mul_f32_e32 v15, v15, v15
	v_mul_f32_e32 v11, v11, v11
	v_mul_f32_e32 v18, v0, v0
	v_mul_f32_e32 v19, v1, v1
	v_mul_f32_e32 v20, v2, v2
	v_mul_f32_e32 v21, v3, v3
	v_cvt_pk_bf16_f32 v0, v12, v13
	v_cvt_pk_bf16_f32 v1, v14, v15
	v_cvt_pk_bf16_f32 v2, v8, v9
	v_cvt_pk_bf16_f32 v3, v10, v11
	v_mul_f32_e32 v4, v4, v4
	v_mul_f32_e32 v5, v5, v5
	v_mul_f32_e32 v6, v6, v6
	v_mul_f32_e32 v7, v7, v7
	global_store_dwordx4 v[16:17], v[0:3], off
	s_nop 1
	v_cvt_pk_bf16_f32 v0, v4, v5
	v_cvt_pk_bf16_f32 v1, v6, v7
	v_cvt_pk_bf16_f32 v2, v18, v19
	v_cvt_pk_bf16_f32 v3, v20, v21
	global_store_dwordx4 v[16:17], v[0:3], off offset:256
	s_cbranch_vccnz .LBB0_691
	s_andn2_b64 vcc, exec, s[2:3]
	s_cbranch_vccnz .LBB0_690
	s_barrier
	s_branch .LBB0_690

.LBB0_1368:
	v_lshl_add_u32 v146, s6, 8, v148
	v_ashrrev_i32_e32 v147, 31, v146
	v_lshlrev_b64 v[144:145], 6, v[146:147]
	v_lshl_add_u64 v[144:145], s[10:11], 0, v[144:145]
	v_bfe_u32 v164, v206, 4, 2
	v_lshlrev_b32_e32 v164, 4, v164
	v_mov_b32_e32 v165, 0
	v_lshl_add_u64 v[160:161], v[144:145], 0, v[164:165]
	global_load_dwordx4 v[184:187], v[160:161], off
	global_load_dwordx4 v[188:191], v[160:161], off offset:1024
	global_load_dwordx4 v[192:195], v[160:161], off offset:2048
	global_load_dwordx4 v[196:199], v[160:161], off offset:3072
	s_mov_b64 s[100:101], 0x2000
	v_lshl_add_u64 v[220:221], v[160:161], 0, s[100:101]
	global_load_dwordx4 v[200:203], v[220:221], off
	global_load_dwordx4 v[208:211], v[220:221], off offset:1024
	global_load_dwordx4 v[212:215], v[220:221], off offset:2048
	global_load_dwordx4 v[216:219], v[220:221], off offset:3072
	v_lshlrev_b64 v[174:175], 13, v[146:147]
	v_lshl_or_b32 v144, s7, 8, v150
	v_ashrrev_i32_e32 v145, 31, v144
	v_or_b32_e32 v172, 16, v146
	v_lshl_add_u64 v[144:145], v[144:145], 1, s[8:9]
	v_ashrrev_i32_e32 v173, 31, v172
	s_waitcnt vmcnt(7)
	v_add_f32_e32 v160, v184, v185
	v_add_f32_e32 v161, v186, v187
	v_add_f32_e32 v160, v160, v161
	ds_swizzle_b32 v161, v160 offset:swizzle(SWAP,16)
	s_waitcnt lgkmcnt(0)
	v_add_f32_e32 v160, v160, v161
	v_mov_b32_e32 v161, v160
	s_nop 1
	v_permlane32_swap_b32_e32 v160, v161
	v_add_f32_e32 v168, v160, v161
	s_nop 0
	v_lshlrev_b64 v[158:159], 6, v[172:173]
	v_mov_b32_e32 v147, v168
	v_fmamk_f32 v147, v147, 0x3a800000, v154
	v_mul_f32_e32 v155, 0x4b800000, v147
	v_cmp_gt_f32_e32 vcc, s48, v147
	v_lshl_add_u64 v[156:157], v[144:145], 0, v[174:175]
	v_lshl_add_u64 v[158:159], s[10:11], 0, v[158:159]
	v_cndmask_b32_e32 v147, v147, v155, vcc
	v_rsq_f32_e32 v147, v147
	s_nop 0
	v_mul_f32_e32 v155, 0x45800000, v147
	v_cndmask_b32_e32 v160, v147, v155, vcc
	v_pk_mul_f32 v[126:127], v[126:127], v[160:161] op_sel_hi:[1,0]
	v_pk_mul_f32 v[124:125], v[124:125], v[160:161] op_sel_hi:[1,0]
	v_pk_mul_f32 v[122:123], v[122:123], v[160:161] op_sel_hi:[1,0]
	v_pk_mul_f32 v[120:121], v[120:121], v[160:161] op_sel_hi:[1,0]
	v_pk_mul_f32 v[114:115], v[114:115], v[160:161] op_sel_hi:[1,0]
	v_pk_mul_f32 v[112:113], v[112:113], v[160:161] op_sel_hi:[1,0]
	v_pk_mul_f32 v[118:119], v[118:119], v[160:161] op_sel_hi:[1,0]
	v_pk_mul_f32 v[116:117], v[116:117], v[160:161] op_sel_hi:[1,0]
	v_max_f32_e32 v124, 0, v124
	v_max_f32_e32 v120, 0, v120
	v_max_f32_e32 v125, 0, v125
	v_max_f32_e32 v121, 0, v121
	v_max_f32_e32 v126, 0, v126
	v_max_f32_e32 v122, 0, v122
	v_max_f32_e32 v127, 0, v127
	v_max_f32_e32 v123, 0, v123
	v_max_f32_e32 v112, 0, v112
	v_max_f32_e32 v113, 0, v113
	v_max_f32_e32 v114, 0, v114
	v_max_f32_e32 v115, 0, v115
	v_max_f32_e32 v116, 0, v116
	v_max_f32_e32 v117, 0, v117
	v_max_f32_e32 v118, 0, v118
	v_max_f32_e32 v119, 0, v119
	v_mul_f32_e32 v124, v124, v124
	v_mul_f32_e32 v120, v120, v120
	v_mul_f32_e32 v125, v125, v125
	v_mul_f32_e32 v121, v121, v121
	v_mul_f32_e32 v126, v126, v126
	v_mul_f32_e32 v122, v122, v122
	v_mul_f32_e32 v127, v127, v127
	v_mul_f32_e32 v123, v123, v123
	v_mul_f32_e32 v147, v112, v112
	v_mul_f32_e32 v155, v113, v113
	v_mul_f32_e32 v160, v114, v114
	v_mul_f32_e32 v161, v115, v115
	v_cvt_pk_bf16_f32 v112, v124, v125
	v_cvt_pk_bf16_f32 v113, v126, v127
	v_cvt_pk_bf16_f32 v114, v120, v121
	v_cvt_pk_bf16_f32 v115, v122, v123
	v_mul_f32_e32 v116, v116, v116
	v_mul_f32_e32 v117, v117, v117
	v_mul_f32_e32 v118, v118, v118
	v_mul_f32_e32 v119, v119, v119
	global_store_dwordx4 v[156:157], v[112:115], off
	s_nop 1
	v_cvt_pk_bf16_f32 v112, v116, v117
	v_cvt_pk_bf16_f32 v113, v118, v119
	v_cvt_pk_bf16_f32 v114, v147, v155
	v_cvt_pk_bf16_f32 v115, v160, v161
	global_store_dwordx4 v[156:157], v[112:115], off offset:256
	s_nop 0
	v_or_b32_e32 v156, 32, v146
	v_ashrrev_i32_e32 v157, 31, v156
	v_lshlrev_b64 v[158:159], 13, v[172:173]
	s_waitcnt vmcnt(8)
	v_add_f32_e32 v116, v188, v189
	v_add_f32_e32 v117, v190, v191
	v_add_f32_e32 v116, v116, v117
	ds_swizzle_b32 v117, v116 offset:swizzle(SWAP,16)
	s_waitcnt lgkmcnt(0)
	v_add_f32_e32 v116, v116, v117
	v_mov_b32_e32 v117, v116
	s_nop 1
	v_permlane32_swap_b32_e32 v116, v117
	v_add_f32_e32 v124, v116, v117
	s_nop 0
	v_lshl_add_u64 v[114:115], v[144:145], 0, v[158:159]
	v_mov_b32_e32 v112, v124
	v_fmamk_f32 v112, v112, 0x3a800000, v154
	v_mul_f32_e32 v113, 0x4b800000, v112
	v_cmp_gt_f32_e32 vcc, s48, v112
	s_nop 1
	v_cndmask_b32_e32 v112, v112, v113, vcc
	v_rsq_f32_e32 v116, v112
	v_lshlrev_b64 v[112:113], 6, v[156:157]
	v_lshl_add_u64 v[112:113], s[10:11], 0, v[112:113]
	v_mul_f32_e32 v117, 0x45800000, v116
	v_cndmask_b32_e32 v116, v116, v117, vcc
	v_pk_mul_f32 v[110:111], v[110:111], v[116:117] op_sel_hi:[1,0]
	v_pk_mul_f32 v[108:109], v[108:109], v[116:117] op_sel_hi:[1,0]
	v_pk_mul_f32 v[106:107], v[106:107], v[116:117] op_sel_hi:[1,0]
	v_pk_mul_f32 v[104:105], v[104:105], v[116:117] op_sel_hi:[1,0]
	v_pk_mul_f32 v[98:99], v[98:99], v[116:117] op_sel_hi:[1,0]
	v_pk_mul_f32 v[96:97], v[96:97], v[116:117] op_sel_hi:[1,0]
	v_pk_mul_f32 v[102:103], v[102:103], v[116:117] op_sel_hi:[1,0]
	v_pk_mul_f32 v[100:101], v[100:101], v[116:117] op_sel_hi:[1,0]
	v_max_f32_e32 v108, 0, v108
	v_max_f32_e32 v104, 0, v104
	v_max_f32_e32 v109, 0, v109
	v_max_f32_e32 v105, 0, v105
	v_max_f32_e32 v110, 0, v110
	v_max_f32_e32 v106, 0, v106
	v_max_f32_e32 v111, 0, v111
	v_max_f32_e32 v107, 0, v107
	v_max_f32_e32 v96, 0, v96
	v_max_f32_e32 v97, 0, v97
	v_max_f32_e32 v98, 0, v98
	v_max_f32_e32 v99, 0, v99
	v_max_f32_e32 v100, 0, v100
	v_max_f32_e32 v101, 0, v101
	v_max_f32_e32 v102, 0, v102
	v_max_f32_e32 v103, 0, v103
	v_mul_f32_e32 v108, v108, v108
	v_mul_f32_e32 v104, v104, v104
	v_mul_f32_e32 v109, v109, v109
	v_mul_f32_e32 v105, v105, v105
	v_mul_f32_e32 v110, v110, v110
	v_mul_f32_e32 v106, v106, v106
	v_mul_f32_e32 v111, v111, v111
	v_mul_f32_e32 v107, v107, v107
	v_mul_f32_e32 v116, v96, v96
	v_mul_f32_e32 v117, v97, v97
	v_mul_f32_e32 v118, v98, v98
	v_mul_f32_e32 v119, v99, v99
	v_cvt_pk_bf16_f32 v96, v108, v109
	v_cvt_pk_bf16_f32 v97, v110, v111
	v_cvt_pk_bf16_f32 v98, v104, v105
	v_cvt_pk_bf16_f32 v99, v106, v107
	v_mul_f32_e32 v100, v100, v100
	v_mul_f32_e32 v101, v101, v101
	v_mul_f32_e32 v102, v102, v102
	v_mul_f32_e32 v103, v103, v103
	global_store_dwordx4 v[114:115], v[96:99], off
	s_nop 1
	v_cvt_pk_bf16_f32 v96, v100, v101
	v_cvt_pk_bf16_f32 v97, v102, v103
	v_cvt_pk_bf16_f32 v98, v116, v117
	v_cvt_pk_bf16_f32 v99, v118, v119
	global_store_dwordx4 v[114:115], v[96:99], off offset:256
	s_nop 0
	v_or_b32_e32 v112, 48, v146
	v_ashrrev_i32_e32 v113, 31, v112
	v_lshlrev_b64 v[114:115], 13, v[156:157]
	s_waitcnt vmcnt(9)
	v_add_f32_e32 v100, v192, v193
	v_add_f32_e32 v101, v194, v195
	v_add_f32_e32 v100, v100, v101
	ds_swizzle_b32 v101, v100 offset:swizzle(SWAP,16)
	s_waitcnt lgkmcnt(0)
	v_add_f32_e32 v100, v100, v101
	v_mov_b32_e32 v101, v100
	s_nop 1
	v_permlane32_swap_b32_e32 v100, v101
	v_add_f32_e32 v108, v100, v101
	s_nop 0
	v_lshl_add_u64 v[98:99], v[144:145], 0, v[114:115]
	v_mov_b32_e32 v96, v108
	v_fmamk_f32 v96, v96, 0x3a800000, v154
	v_mul_f32_e32 v97, 0x4b800000, v96
	v_cmp_gt_f32_e32 vcc, s48, v96
	s_nop 1
	v_cndmask_b32_e32 v96, v96, v97, vcc
	v_rsq_f32_e32 v100, v96
	v_lshlrev_b64 v[96:97], 6, v[112:113]
	v_lshl_add_u64 v[96:97], s[10:11], 0, v[96:97]
	v_mul_f32_e32 v101, 0x45800000, v100
	v_cndmask_b32_e32 v100, v100, v101, vcc
	v_pk_mul_f32 v[94:95], v[94:95], v[100:101] op_sel_hi:[1,0]
	v_pk_mul_f32 v[92:93], v[92:93], v[100:101] op_sel_hi:[1,0]
	v_pk_mul_f32 v[90:91], v[90:91], v[100:101] op_sel_hi:[1,0]
	v_pk_mul_f32 v[88:89], v[88:89], v[100:101] op_sel_hi:[1,0]
	v_pk_mul_f32 v[82:83], v[82:83], v[100:101] op_sel_hi:[1,0]
	v_pk_mul_f32 v[80:81], v[80:81], v[100:101] op_sel_hi:[1,0]
	v_pk_mul_f32 v[86:87], v[86:87], v[100:101] op_sel_hi:[1,0]
	v_pk_mul_f32 v[84:85], v[84:85], v[100:101] op_sel_hi:[1,0]
	v_max_f32_e32 v92, 0, v92
	v_max_f32_e32 v88, 0, v88
	v_max_f32_e32 v93, 0, v93
	v_max_f32_e32 v89, 0, v89
	v_max_f32_e32 v94, 0, v94
	v_max_f32_e32 v90, 0, v90
	v_max_f32_e32 v95, 0, v95
	v_max_f32_e32 v91, 0, v91
	v_max_f32_e32 v80, 0, v80
	v_max_f32_e32 v81, 0, v81
	v_max_f32_e32 v82, 0, v82
	v_max_f32_e32 v83, 0, v83
	v_max_f32_e32 v84, 0, v84
	v_max_f32_e32 v85, 0, v85
	v_max_f32_e32 v86, 0, v86
	v_max_f32_e32 v87, 0, v87
	v_mul_f32_e32 v92, v92, v92
	v_mul_f32_e32 v88, v88, v88
	v_mul_f32_e32 v93, v93, v93
	v_mul_f32_e32 v89, v89, v89
	v_mul_f32_e32 v94, v94, v94
	v_mul_f32_e32 v90, v90, v90
	v_mul_f32_e32 v95, v95, v95
	v_mul_f32_e32 v91, v91, v91
	v_mul_f32_e32 v100, v80, v80
	v_mul_f32_e32 v101, v81, v81
	v_mul_f32_e32 v102, v82, v82
	v_mul_f32_e32 v103, v83, v83
	v_cvt_pk_bf16_f32 v80, v92, v93
	v_cvt_pk_bf16_f32 v81, v94, v95
	v_cvt_pk_bf16_f32 v82, v88, v89
	v_cvt_pk_bf16_f32 v83, v90, v91
	v_mul_f32_e32 v84, v84, v84
	v_mul_f32_e32 v85, v85, v85
	v_mul_f32_e32 v86, v86, v86
	v_mul_f32_e32 v87, v87, v87
	global_store_dwordx4 v[98:99], v[80:83], off
	s_nop 1
	v_cvt_pk_bf16_f32 v80, v84, v85
	v_cvt_pk_bf16_f32 v81, v86, v87
	v_cvt_pk_bf16_f32 v82, v100, v101
	v_cvt_pk_bf16_f32 v83, v102, v103
	global_store_dwordx4 v[98:99], v[80:83], off offset:256
	s_nop 0
	v_add_u32_e32 v96, 0x80, v146
	v_ashrrev_i32_e32 v97, 31, v96
	v_lshlrev_b64 v[98:99], 13, v[112:113]
	s_waitcnt vmcnt(10)
	v_add_f32_e32 v84, v196, v197
	v_add_f32_e32 v85, v198, v199
	v_add_f32_e32 v84, v84, v85
	ds_swizzle_b32 v85, v84 offset:swizzle(SWAP,16)
	s_waitcnt lgkmcnt(0)
	v_add_f32_e32 v84, v84, v85
	v_mov_b32_e32 v85, v84
	s_nop 1
	v_permlane32_swap_b32_e32 v84, v85
	v_add_f32_e32 v92, v84, v85
	s_nop 0
	v_lshl_add_u64 v[82:83], v[144:145], 0, v[98:99]
	v_mov_b32_e32 v80, v92
	v_fmamk_f32 v80, v80, 0x3a800000, v154
	v_mul_f32_e32 v81, 0x4b800000, v80
	v_cmp_gt_f32_e32 vcc, s48, v80
	s_nop 1
	v_cndmask_b32_e32 v80, v80, v81, vcc
	v_rsq_f32_e32 v84, v80
	v_lshlrev_b64 v[80:81], 6, v[96:97]
	v_lshl_add_u64 v[80:81], s[10:11], 0, v[80:81]
	v_mul_f32_e32 v85, 0x45800000, v84
	v_cndmask_b32_e32 v84, v84, v85, vcc
	v_pk_mul_f32 v[78:79], v[78:79], v[84:85] op_sel_hi:[1,0]
	v_pk_mul_f32 v[76:77], v[76:77], v[84:85] op_sel_hi:[1,0]
	v_pk_mul_f32 v[74:75], v[74:75], v[84:85] op_sel_hi:[1,0]
	v_pk_mul_f32 v[72:73], v[72:73], v[84:85] op_sel_hi:[1,0]
	v_pk_mul_f32 v[66:67], v[66:67], v[84:85] op_sel_hi:[1,0]
	v_pk_mul_f32 v[64:65], v[64:65], v[84:85] op_sel_hi:[1,0]
	v_pk_mul_f32 v[70:71], v[70:71], v[84:85] op_sel_hi:[1,0]
	v_pk_mul_f32 v[68:69], v[68:69], v[84:85] op_sel_hi:[1,0]
	v_max_f32_e32 v76, 0, v76
	v_max_f32_e32 v72, 0, v72
	v_max_f32_e32 v77, 0, v77
	v_max_f32_e32 v73, 0, v73
	v_max_f32_e32 v78, 0, v78
	v_max_f32_e32 v74, 0, v74
	v_max_f32_e32 v79, 0, v79
	v_max_f32_e32 v75, 0, v75
	v_max_f32_e32 v64, 0, v64
	v_max_f32_e32 v65, 0, v65
	v_max_f32_e32 v66, 0, v66
	v_max_f32_e32 v67, 0, v67
	v_max_f32_e32 v68, 0, v68
	v_max_f32_e32 v69, 0, v69
	v_max_f32_e32 v70, 0, v70
	v_max_f32_e32 v71, 0, v71
	v_mul_f32_e32 v76, v76, v76
	v_mul_f32_e32 v72, v72, v72
	v_mul_f32_e32 v77, v77, v77
	v_mul_f32_e32 v73, v73, v73
	v_mul_f32_e32 v78, v78, v78
	v_mul_f32_e32 v74, v74, v74
	v_mul_f32_e32 v79, v79, v79
	v_mul_f32_e32 v75, v75, v75
	v_mul_f32_e32 v84, v64, v64
	v_mul_f32_e32 v85, v65, v65
	v_mul_f32_e32 v86, v66, v66
	v_mul_f32_e32 v87, v67, v67
	v_cvt_pk_bf16_f32 v64, v76, v77
	v_cvt_pk_bf16_f32 v65, v78, v79
	v_cvt_pk_bf16_f32 v66, v72, v73
	v_cvt_pk_bf16_f32 v67, v74, v75
	v_mul_f32_e32 v68, v68, v68
	v_mul_f32_e32 v69, v69, v69
	v_mul_f32_e32 v70, v70, v70
	v_mul_f32_e32 v71, v71, v71
	global_store_dwordx4 v[82:83], v[64:67], off
	s_nop 1
	v_cvt_pk_bf16_f32 v64, v68, v69
	v_cvt_pk_bf16_f32 v65, v70, v71
	v_cvt_pk_bf16_f32 v66, v84, v85
	v_cvt_pk_bf16_f32 v67, v86, v87
	global_store_dwordx4 v[82:83], v[64:67], off offset:256
	s_nop 0
	v_add_u32_e32 v80, 0x90, v146
	v_ashrrev_i32_e32 v81, 31, v80
	v_lshlrev_b64 v[82:83], 13, v[96:97]
	s_waitcnt vmcnt(11)
	v_add_f32_e32 v68, v200, v201
	v_add_f32_e32 v69, v202, v203
	v_add_f32_e32 v68, v68, v69
	ds_swizzle_b32 v69, v68 offset:swizzle(SWAP,16)
	s_waitcnt lgkmcnt(0)
	v_add_f32_e32 v68, v68, v69
	v_mov_b32_e32 v69, v68
	s_nop 1
	v_permlane32_swap_b32_e32 v68, v69
	v_add_f32_e32 v76, v68, v69
	s_nop 0
	v_lshl_add_u64 v[66:67], v[144:145], 0, v[82:83]
	v_mov_b32_e32 v64, v76
	v_fmamk_f32 v64, v64, 0x3a800000, v154
	v_mul_f32_e32 v65, 0x4b800000, v64
	v_cmp_gt_f32_e32 vcc, s48, v64
	s_nop 1
	v_cndmask_b32_e32 v64, v64, v65, vcc
	v_rsq_f32_e32 v68, v64
	v_lshlrev_b64 v[64:65], 6, v[80:81]
	v_lshl_add_u64 v[64:65], s[10:11], 0, v[64:65]
	v_mul_f32_e32 v69, 0x45800000, v68
	v_cndmask_b32_e32 v68, v68, v69, vcc
	v_pk_mul_f32 v[62:63], v[62:63], v[68:69] op_sel_hi:[1,0]
	v_pk_mul_f32 v[60:61], v[60:61], v[68:69] op_sel_hi:[1,0]
	v_pk_mul_f32 v[58:59], v[58:59], v[68:69] op_sel_hi:[1,0]
	v_pk_mul_f32 v[56:57], v[56:57], v[68:69] op_sel_hi:[1,0]
	v_pk_mul_f32 v[50:51], v[50:51], v[68:69] op_sel_hi:[1,0]
	v_pk_mul_f32 v[48:49], v[48:49], v[68:69] op_sel_hi:[1,0]
	v_pk_mul_f32 v[54:55], v[54:55], v[68:69] op_sel_hi:[1,0]
	v_pk_mul_f32 v[52:53], v[52:53], v[68:69] op_sel_hi:[1,0]
	v_max_f32_e32 v60, 0, v60
	v_max_f32_e32 v56, 0, v56
	v_max_f32_e32 v61, 0, v61
	v_max_f32_e32 v57, 0, v57
	v_max_f32_e32 v62, 0, v62
	v_max_f32_e32 v58, 0, v58
	v_max_f32_e32 v63, 0, v63
	v_max_f32_e32 v59, 0, v59
	v_max_f32_e32 v48, 0, v48
	v_max_f32_e32 v49, 0, v49
	v_max_f32_e32 v50, 0, v50
	v_max_f32_e32 v51, 0, v51
	v_max_f32_e32 v52, 0, v52
	v_max_f32_e32 v53, 0, v53
	v_max_f32_e32 v54, 0, v54
	v_max_f32_e32 v55, 0, v55
	v_mul_f32_e32 v60, v60, v60
	v_mul_f32_e32 v56, v56, v56
	v_mul_f32_e32 v61, v61, v61
	v_mul_f32_e32 v57, v57, v57
	v_mul_f32_e32 v62, v62, v62
	v_mul_f32_e32 v58, v58, v58
	v_mul_f32_e32 v63, v63, v63
	v_mul_f32_e32 v59, v59, v59
	v_mul_f32_e32 v68, v48, v48
	v_mul_f32_e32 v69, v49, v49
	v_mul_f32_e32 v70, v50, v50
	v_mul_f32_e32 v71, v51, v51
	v_cvt_pk_bf16_f32 v48, v60, v61
	v_cvt_pk_bf16_f32 v49, v62, v63
	v_cvt_pk_bf16_f32 v50, v56, v57
	v_cvt_pk_bf16_f32 v51, v58, v59
	v_mul_f32_e32 v52, v52, v52
	v_mul_f32_e32 v53, v53, v53
	v_mul_f32_e32 v54, v54, v54
	v_mul_f32_e32 v55, v55, v55
	global_store_dwordx4 v[66:67], v[48:51], off
	s_nop 1
	v_cvt_pk_bf16_f32 v48, v52, v53
	v_cvt_pk_bf16_f32 v49, v54, v55
	v_cvt_pk_bf16_f32 v50, v68, v69
	v_cvt_pk_bf16_f32 v51, v70, v71
	global_store_dwordx4 v[66:67], v[48:51], off offset:256
	s_nop 0
	v_add_u32_e32 v64, 0xa0, v146
	v_ashrrev_i32_e32 v65, 31, v64
	v_lshlrev_b64 v[66:67], 13, v[80:81]
	s_waitcnt vmcnt(12)
	v_add_f32_e32 v52, v208, v209
	v_add_f32_e32 v53, v210, v211
	v_add_f32_e32 v52, v52, v53
	ds_swizzle_b32 v53, v52 offset:swizzle(SWAP,16)
	s_waitcnt lgkmcnt(0)
	v_add_f32_e32 v52, v52, v53
	v_mov_b32_e32 v53, v52
	s_nop 1
	v_permlane32_swap_b32_e32 v52, v53
	v_add_f32_e32 v60, v52, v53
	s_nop 0
	v_lshl_add_u64 v[50:51], v[144:145], 0, v[66:67]
	v_mov_b32_e32 v48, v60
	v_fmamk_f32 v48, v48, 0x3a800000, v154
	v_mul_f32_e32 v49, 0x4b800000, v48
	v_cmp_gt_f32_e32 vcc, s48, v48
	s_nop 1
	v_cndmask_b32_e32 v48, v48, v49, vcc
	v_rsq_f32_e32 v52, v48
	v_lshlrev_b64 v[48:49], 6, v[64:65]
	v_lshl_add_u64 v[48:49], s[10:11], 0, v[48:49]
	v_mul_f32_e32 v53, 0x45800000, v52
	v_cndmask_b32_e32 v52, v52, v53, vcc
	v_pk_mul_f32 v[46:47], v[46:47], v[52:53] op_sel_hi:[1,0]
	v_pk_mul_f32 v[44:45], v[44:45], v[52:53] op_sel_hi:[1,0]
	v_pk_mul_f32 v[42:43], v[42:43], v[52:53] op_sel_hi:[1,0]
	v_pk_mul_f32 v[40:41], v[40:41], v[52:53] op_sel_hi:[1,0]
	v_pk_mul_f32 v[34:35], v[34:35], v[52:53] op_sel_hi:[1,0]
	v_pk_mul_f32 v[32:33], v[32:33], v[52:53] op_sel_hi:[1,0]
	v_pk_mul_f32 v[38:39], v[38:39], v[52:53] op_sel_hi:[1,0]
	v_pk_mul_f32 v[36:37], v[36:37], v[52:53] op_sel_hi:[1,0]
	v_max_f32_e32 v44, 0, v44
	v_max_f32_e32 v40, 0, v40
	v_max_f32_e32 v45, 0, v45
	v_max_f32_e32 v41, 0, v41
	v_max_f32_e32 v46, 0, v46
	v_max_f32_e32 v42, 0, v42
	v_max_f32_e32 v47, 0, v47
	v_max_f32_e32 v43, 0, v43
	v_max_f32_e32 v32, 0, v32
	v_max_f32_e32 v33, 0, v33
	v_max_f32_e32 v34, 0, v34
	v_max_f32_e32 v35, 0, v35
	v_max_f32_e32 v36, 0, v36
	v_max_f32_e32 v37, 0, v37
	v_max_f32_e32 v38, 0, v38
	v_max_f32_e32 v39, 0, v39
	v_mul_f32_e32 v44, v44, v44
	v_mul_f32_e32 v40, v40, v40
	v_mul_f32_e32 v45, v45, v45
	v_mul_f32_e32 v41, v41, v41
	v_mul_f32_e32 v46, v46, v46
	v_mul_f32_e32 v42, v42, v42
	v_mul_f32_e32 v47, v47, v47
	v_mul_f32_e32 v43, v43, v43
	v_mul_f32_e32 v52, v32, v32
	v_mul_f32_e32 v53, v33, v33
	v_mul_f32_e32 v54, v34, v34
	v_mul_f32_e32 v55, v35, v35
	v_cvt_pk_bf16_f32 v32, v44, v45
	v_cvt_pk_bf16_f32 v33, v46, v47
	v_cvt_pk_bf16_f32 v34, v40, v41
	v_cvt_pk_bf16_f32 v35, v42, v43
	v_mul_f32_e32 v36, v36, v36
	v_mul_f32_e32 v37, v37, v37
	v_mul_f32_e32 v38, v38, v38
	v_mul_f32_e32 v39, v39, v39
	global_store_dwordx4 v[50:51], v[32:35], off
	s_nop 1
	v_cvt_pk_bf16_f32 v32, v36, v37
	v_cvt_pk_bf16_f32 v33, v38, v39
	v_cvt_pk_bf16_f32 v34, v52, v53
	v_cvt_pk_bf16_f32 v35, v54, v55
	global_store_dwordx4 v[50:51], v[32:35], off offset:256
	s_nop 0
	v_add_u32_e32 v48, 0xb0, v146
	v_ashrrev_i32_e32 v49, 31, v48
	v_lshlrev_b64 v[50:51], 13, v[64:65]
	s_waitcnt vmcnt(13)
	v_add_f32_e32 v36, v212, v213
	v_add_f32_e32 v37, v214, v215
	v_add_f32_e32 v36, v36, v37
	ds_swizzle_b32 v37, v36 offset:swizzle(SWAP,16)
	s_waitcnt lgkmcnt(0)
	v_add_f32_e32 v36, v36, v37
	v_mov_b32_e32 v37, v36
	s_nop 1
	v_permlane32_swap_b32_e32 v36, v37
	v_add_f32_e32 v44, v36, v37
	s_nop 0
	v_lshl_add_u64 v[34:35], v[144:145], 0, v[50:51]
	v_mov_b32_e32 v32, v44
	v_fmamk_f32 v32, v32, 0x3a800000, v154
	v_mul_f32_e32 v33, 0x4b800000, v32
	v_cmp_gt_f32_e32 vcc, s48, v32
	s_nop 1
	v_cndmask_b32_e32 v32, v32, v33, vcc
	v_rsq_f32_e32 v36, v32
	v_lshlrev_b64 v[32:33], 6, v[48:49]
	v_lshl_add_u64 v[32:33], s[10:11], 0, v[32:33]
	v_mul_f32_e32 v37, 0x45800000, v36
	v_cndmask_b32_e32 v36, v36, v37, vcc
	v_pk_mul_f32 v[30:31], v[30:31], v[36:37] op_sel_hi:[1,0]
	v_pk_mul_f32 v[28:29], v[28:29], v[36:37] op_sel_hi:[1,0]
	v_pk_mul_f32 v[26:27], v[26:27], v[36:37] op_sel_hi:[1,0]
	v_pk_mul_f32 v[24:25], v[24:25], v[36:37] op_sel_hi:[1,0]
	v_pk_mul_f32 v[18:19], v[18:19], v[36:37] op_sel_hi:[1,0]
	v_pk_mul_f32 v[16:17], v[16:17], v[36:37] op_sel_hi:[1,0]
	v_pk_mul_f32 v[22:23], v[22:23], v[36:37] op_sel_hi:[1,0]
	v_pk_mul_f32 v[20:21], v[20:21], v[36:37] op_sel_hi:[1,0]
	v_max_f32_e32 v28, 0, v28
	v_max_f32_e32 v24, 0, v24
	v_max_f32_e32 v29, 0, v29
	v_max_f32_e32 v25, 0, v25
	v_max_f32_e32 v30, 0, v30
	v_max_f32_e32 v26, 0, v26
	v_max_f32_e32 v31, 0, v31
	v_max_f32_e32 v27, 0, v27
	v_max_f32_e32 v16, 0, v16
	v_max_f32_e32 v17, 0, v17
	v_max_f32_e32 v18, 0, v18
	v_max_f32_e32 v19, 0, v19
	v_max_f32_e32 v20, 0, v20
	v_max_f32_e32 v21, 0, v21
	v_max_f32_e32 v22, 0, v22
	v_max_f32_e32 v23, 0, v23
	v_mul_f32_e32 v28, v28, v28
	v_mul_f32_e32 v24, v24, v24
	v_mul_f32_e32 v29, v29, v29
	v_mul_f32_e32 v25, v25, v25
	v_mul_f32_e32 v30, v30, v30
	v_mul_f32_e32 v26, v26, v26
	v_mul_f32_e32 v31, v31, v31
	v_mul_f32_e32 v27, v27, v27
	v_mul_f32_e32 v36, v16, v16
	v_mul_f32_e32 v37, v17, v17
	v_mul_f32_e32 v38, v18, v18
	v_mul_f32_e32 v39, v19, v19
	v_cvt_pk_bf16_f32 v16, v28, v29
	v_cvt_pk_bf16_f32 v17, v30, v31
	v_cvt_pk_bf16_f32 v18, v24, v25
	v_cvt_pk_bf16_f32 v19, v26, v27
	v_mul_f32_e32 v20, v20, v20
	v_mul_f32_e32 v21, v21, v21
	v_mul_f32_e32 v22, v22, v22
	v_mul_f32_e32 v23, v23, v23
	global_store_dwordx4 v[34:35], v[16:19], off
	s_andn2_b64 vcc, exec, s[4:5]
	s_mov_b64 s[4:5], -1
	v_cvt_pk_bf16_f32 v16, v20, v21
	v_cvt_pk_bf16_f32 v17, v22, v23
	v_cvt_pk_bf16_f32 v18, v36, v37
	v_cvt_pk_bf16_f32 v19, v38, v39
	global_store_dwordx4 v[34:35], v[16:19], off offset:256
	s_nop 0
	s_waitcnt vmcnt(14)
	v_add_f32_e32 v20, v216, v217
	v_add_f32_e32 v21, v218, v219
	v_add_f32_e32 v20, v20, v21
	ds_swizzle_b32 v21, v20 offset:swizzle(SWAP,16)
	s_waitcnt lgkmcnt(0)
	v_add_f32_e32 v20, v20, v21
	v_mov_b32_e32 v21, v20
	s_nop 1
	v_permlane32_swap_b32_e32 v20, v21
	v_add_f32_e32 v28, v20, v21
	s_nop 0
	s_nop 0
	v_mov_b32_e32 v16, v28
	v_fmamk_f32 v16, v16, 0x3a800000, v154
	v_mul_f32_e32 v17, 0x4b800000, v16
	v_cmp_gt_f32_e64 s[6:7], s48, v16
	s_nop 1
	v_cndmask_b32_e64 v16, v16, v17, s[6:7]
	v_rsq_f32_e32 v18, v16
	v_lshlrev_b64 v[16:17], 13, v[48:49]
	v_lshl_add_u64 v[16:17], v[144:145], 0, v[16:17]
	v_mul_f32_e32 v19, 0x45800000, v18
	v_cndmask_b32_e64 v18, v18, v19, s[6:7]
	v_pk_mul_f32 v[14:15], v[14:15], v[18:19] op_sel_hi:[1,0]
	v_pk_mul_f32 v[12:13], v[12:13], v[18:19] op_sel_hi:[1,0]
	v_pk_mul_f32 v[10:11], v[10:11], v[18:19] op_sel_hi:[1,0]
	v_pk_mul_f32 v[8:9], v[8:9], v[18:19] op_sel_hi:[1,0]
	v_pk_mul_f32 v[2:3], v[2:3], v[18:19] op_sel_hi:[1,0]
	v_pk_mul_f32 v[0:1], v[0:1], v[18:19] op_sel_hi:[1,0]
	v_pk_mul_f32 v[6:7], v[6:7], v[18:19] op_sel_hi:[1,0]
	v_pk_mul_f32 v[4:5], v[4:5], v[18:19] op_sel_hi:[1,0]
	v_max_f32_e32 v12, 0, v12
	v_max_f32_e32 v8, 0, v8
	v_max_f32_e32 v13, 0, v13
	v_max_f32_e32 v9, 0, v9
	v_max_f32_e32 v14, 0, v14
	v_max_f32_e32 v10, 0, v10
	v_max_f32_e32 v15, 0, v15
	v_max_f32_e32 v11, 0, v11
	v_max_f32_e32 v0, 0, v0
	v_max_f32_e32 v1, 0, v1
	v_max_f32_e32 v2, 0, v2
	v_max_f32_e32 v3, 0, v3
	v_max_f32_e32 v4, 0, v4
	v_max_f32_e32 v5, 0, v5
	v_max_f32_e32 v6, 0, v6
	v_max_f32_e32 v7, 0, v7
	v_mul_f32_e32 v12, v12, v12
	v_mul_f32_e32 v8, v8, v8
	v_mul_f32_e32 v13, v13, v13
	v_mul_f32_e32 v9, v9, v9
	v_mul_f32_e32 v14, v14, v14
	v_mul_f32_e32 v10, v10, v10
	v_mul_f32_e32 v15, v15, v15
	v_mul_f32_e32 v11, v11, v11
	v_mul_f32_e32 v18, v0, v0
	v_mul_f32_e32 v19, v1, v1
	v_mul_f32_e32 v20, v2, v2
	v_mul_f32_e32 v21, v3, v3
	v_cvt_pk_bf16_f32 v0, v12, v13
	v_cvt_pk_bf16_f32 v1, v14, v15
	v_cvt_pk_bf16_f32 v2, v8, v9
	v_cvt_pk_bf16_f32 v3, v10, v11
	v_mul_f32_e32 v4, v4, v4
	v_mul_f32_e32 v5, v5, v5
	v_mul_f32_e32 v6, v6, v6
	v_mul_f32_e32 v7, v7, v7
	global_store_dwordx4 v[16:17], v[0:3], off
	s_nop 1
	v_cvt_pk_bf16_f32 v0, v4, v5
	v_cvt_pk_bf16_f32 v1, v6, v7
	v_cvt_pk_bf16_f32 v2, v18, v19
	v_cvt_pk_bf16_f32 v3, v20, v21
	global_store_dwordx4 v[16:17], v[0:3], off offset:256
	s_cbranch_vccnz .LBB0_1357
	s_andn2_b64 vcc, exec, s[2:3]
	s_cbranch_vccnz .LBB0_1356
	s_barrier
	s_branch .LBB0_1356

.LBB0_2182:
	v_lshl_add_u32 v146, s6, 8, v148
	v_ashrrev_i32_e32 v147, 31, v146
	v_lshlrev_b64 v[144:145], 6, v[146:147]
	v_lshl_add_u64 v[144:145], s[10:11], 0, v[144:145]
	v_bfe_u32 v164, v206, 4, 2
	v_lshlrev_b32_e32 v164, 4, v164
	v_mov_b32_e32 v165, 0
	v_lshl_add_u64 v[160:161], v[144:145], 0, v[164:165]
	global_load_dwordx4 v[176:179], v[160:161], off
	global_load_dwordx4 v[180:183], v[160:161], off offset:1024
	global_load_dwordx4 v[184:187], v[160:161], off offset:2048
	global_load_dwordx4 v[188:191], v[160:161], off offset:3072
	s_mov_b64 s[100:101], 0x2000
	v_lshl_add_u64 v[212:213], v[160:161], 0, s[100:101]
	global_load_dwordx4 v[192:195], v[212:213], off
	global_load_dwordx4 v[196:199], v[212:213], off offset:1024
	global_load_dwordx4 v[200:203], v[212:213], off offset:2048
	global_load_dwordx4 v[208:211], v[212:213], off offset:3072
	v_lshlrev_b64 v[174:175], 13, v[146:147]
	v_lshl_or_b32 v144, s7, 8, v150
	v_ashrrev_i32_e32 v145, 31, v144
	v_or_b32_e32 v172, 16, v146
	v_lshl_add_u64 v[144:145], v[144:145], 1, s[12:13]
	v_ashrrev_i32_e32 v173, 31, v172
	s_waitcnt vmcnt(7)
	v_add_f32_e32 v160, v176, v177
	v_add_f32_e32 v161, v178, v179
	v_add_f32_e32 v160, v160, v161
	ds_swizzle_b32 v161, v160 offset:swizzle(SWAP,16)
	s_waitcnt lgkmcnt(0)
	v_add_f32_e32 v160, v160, v161
	v_mov_b32_e32 v161, v160
	s_nop 1
	v_permlane32_swap_b32_e32 v160, v161
	v_add_f32_e32 v168, v160, v161
	s_nop 0
	v_lshlrev_b64 v[158:159], 6, v[172:173]
	v_mov_b32_e32 v147, v168
	v_fmamk_f32 v147, v147, 0x3a800000, v154
	v_mul_f32_e32 v155, 0x4b800000, v147
	v_cmp_gt_f32_e32 vcc, s48, v147
	v_lshl_add_u64 v[156:157], v[144:145], 0, v[174:175]
	v_lshl_add_u64 v[158:159], s[10:11], 0, v[158:159]
	v_cndmask_b32_e32 v147, v147, v155, vcc
	v_rsq_f32_e32 v147, v147
	s_nop 0
	v_mul_f32_e32 v155, 0x45800000, v147
	v_cndmask_b32_e32 v160, v147, v155, vcc
	v_pk_mul_f32 v[126:127], v[126:127], v[160:161] op_sel_hi:[1,0]
	v_pk_mul_f32 v[124:125], v[124:125], v[160:161] op_sel_hi:[1,0]
	v_pk_mul_f32 v[122:123], v[122:123], v[160:161] op_sel_hi:[1,0]
	v_pk_mul_f32 v[120:121], v[120:121], v[160:161] op_sel_hi:[1,0]
	v_pk_mul_f32 v[114:115], v[114:115], v[160:161] op_sel_hi:[1,0]
	v_pk_mul_f32 v[112:113], v[112:113], v[160:161] op_sel_hi:[1,0]
	v_pk_mul_f32 v[118:119], v[118:119], v[160:161] op_sel_hi:[1,0]
	v_pk_mul_f32 v[116:117], v[116:117], v[160:161] op_sel_hi:[1,0]
	v_max_f32_e32 v124, 0, v124
	v_max_f32_e32 v120, 0, v120
	v_max_f32_e32 v125, 0, v125
	v_max_f32_e32 v121, 0, v121
	v_max_f32_e32 v126, 0, v126
	v_max_f32_e32 v122, 0, v122
	v_max_f32_e32 v127, 0, v127
	v_max_f32_e32 v123, 0, v123
	v_max_f32_e32 v112, 0, v112
	v_max_f32_e32 v113, 0, v113
	v_max_f32_e32 v114, 0, v114
	v_max_f32_e32 v115, 0, v115
	v_max_f32_e32 v116, 0, v116
	v_max_f32_e32 v117, 0, v117
	v_max_f32_e32 v118, 0, v118
	v_max_f32_e32 v119, 0, v119
	v_mul_f32_e32 v124, v124, v124
	v_mul_f32_e32 v120, v120, v120
	v_mul_f32_e32 v125, v125, v125
	v_mul_f32_e32 v121, v121, v121
	v_mul_f32_e32 v126, v126, v126
	v_mul_f32_e32 v122, v122, v122
	v_mul_f32_e32 v127, v127, v127
	v_mul_f32_e32 v123, v123, v123
	v_mul_f32_e32 v147, v112, v112
	v_mul_f32_e32 v155, v113, v113
	v_mul_f32_e32 v160, v114, v114
	v_mul_f32_e32 v161, v115, v115
	v_cvt_pk_bf16_f32 v112, v124, v125
	v_cvt_pk_bf16_f32 v113, v126, v127
	v_cvt_pk_bf16_f32 v114, v120, v121
	v_cvt_pk_bf16_f32 v115, v122, v123
	v_mul_f32_e32 v116, v116, v116
	v_mul_f32_e32 v117, v117, v117
	v_mul_f32_e32 v118, v118, v118
	v_mul_f32_e32 v119, v119, v119
	global_store_dwordx4 v[156:157], v[112:115], off
	s_nop 1
	v_cvt_pk_bf16_f32 v112, v116, v117
	v_cvt_pk_bf16_f32 v113, v118, v119
	v_cvt_pk_bf16_f32 v114, v147, v155
	v_cvt_pk_bf16_f32 v115, v160, v161
	global_store_dwordx4 v[156:157], v[112:115], off offset:256
	s_nop 0
	v_or_b32_e32 v156, 32, v146
	v_ashrrev_i32_e32 v157, 31, v156
	v_lshlrev_b64 v[158:159], 13, v[172:173]
	s_waitcnt vmcnt(8)
	v_add_f32_e32 v116, v180, v181
	v_add_f32_e32 v117, v182, v183
	v_add_f32_e32 v116, v116, v117
	ds_swizzle_b32 v117, v116 offset:swizzle(SWAP,16)
	s_waitcnt lgkmcnt(0)
	v_add_f32_e32 v116, v116, v117
	v_mov_b32_e32 v117, v116
	s_nop 1
	v_permlane32_swap_b32_e32 v116, v117
	v_add_f32_e32 v124, v116, v117
	s_nop 0
	v_lshl_add_u64 v[114:115], v[144:145], 0, v[158:159]
	v_mov_b32_e32 v112, v124
	v_fmamk_f32 v112, v112, 0x3a800000, v154
	v_mul_f32_e32 v113, 0x4b800000, v112
	v_cmp_gt_f32_e32 vcc, s48, v112
	s_nop 1
	v_cndmask_b32_e32 v112, v112, v113, vcc
	v_rsq_f32_e32 v116, v112
	v_lshlrev_b64 v[112:113], 6, v[156:157]
	v_lshl_add_u64 v[112:113], s[10:11], 0, v[112:113]
	v_mul_f32_e32 v117, 0x45800000, v116
	v_cndmask_b32_e32 v116, v116, v117, vcc
	v_pk_mul_f32 v[110:111], v[110:111], v[116:117] op_sel_hi:[1,0]
	v_pk_mul_f32 v[108:109], v[108:109], v[116:117] op_sel_hi:[1,0]
	v_pk_mul_f32 v[106:107], v[106:107], v[116:117] op_sel_hi:[1,0]
	v_pk_mul_f32 v[104:105], v[104:105], v[116:117] op_sel_hi:[1,0]
	v_pk_mul_f32 v[98:99], v[98:99], v[116:117] op_sel_hi:[1,0]
	v_pk_mul_f32 v[96:97], v[96:97], v[116:117] op_sel_hi:[1,0]
	v_pk_mul_f32 v[102:103], v[102:103], v[116:117] op_sel_hi:[1,0]
	v_pk_mul_f32 v[100:101], v[100:101], v[116:117] op_sel_hi:[1,0]
	v_max_f32_e32 v108, 0, v108
	v_max_f32_e32 v104, 0, v104
	v_max_f32_e32 v109, 0, v109
	v_max_f32_e32 v105, 0, v105
	v_max_f32_e32 v110, 0, v110
	v_max_f32_e32 v106, 0, v106
	v_max_f32_e32 v111, 0, v111
	v_max_f32_e32 v107, 0, v107
	v_max_f32_e32 v96, 0, v96
	v_max_f32_e32 v97, 0, v97
	v_max_f32_e32 v98, 0, v98
	v_max_f32_e32 v99, 0, v99
	v_max_f32_e32 v100, 0, v100
	v_max_f32_e32 v101, 0, v101
	v_max_f32_e32 v102, 0, v102
	v_max_f32_e32 v103, 0, v103
	v_mul_f32_e32 v108, v108, v108
	v_mul_f32_e32 v104, v104, v104
	v_mul_f32_e32 v109, v109, v109
	v_mul_f32_e32 v105, v105, v105
	v_mul_f32_e32 v110, v110, v110
	v_mul_f32_e32 v106, v106, v106
	v_mul_f32_e32 v111, v111, v111
	v_mul_f32_e32 v107, v107, v107
	v_mul_f32_e32 v116, v96, v96
	v_mul_f32_e32 v117, v97, v97
	v_mul_f32_e32 v118, v98, v98
	v_mul_f32_e32 v119, v99, v99
	v_cvt_pk_bf16_f32 v96, v108, v109
	v_cvt_pk_bf16_f32 v97, v110, v111
	v_cvt_pk_bf16_f32 v98, v104, v105
	v_cvt_pk_bf16_f32 v99, v106, v107
	v_mul_f32_e32 v100, v100, v100
	v_mul_f32_e32 v101, v101, v101
	v_mul_f32_e32 v102, v102, v102
	v_mul_f32_e32 v103, v103, v103
	global_store_dwordx4 v[114:115], v[96:99], off
	s_nop 1
	v_cvt_pk_bf16_f32 v96, v100, v101
	v_cvt_pk_bf16_f32 v97, v102, v103
	v_cvt_pk_bf16_f32 v98, v116, v117
	v_cvt_pk_bf16_f32 v99, v118, v119
	global_store_dwordx4 v[114:115], v[96:99], off offset:256
	s_nop 0
	v_or_b32_e32 v112, 48, v146
	v_ashrrev_i32_e32 v113, 31, v112
	v_lshlrev_b64 v[114:115], 13, v[156:157]
	s_waitcnt vmcnt(9)
	v_add_f32_e32 v100, v184, v185
	v_add_f32_e32 v101, v186, v187
	v_add_f32_e32 v100, v100, v101
	ds_swizzle_b32 v101, v100 offset:swizzle(SWAP,16)
	s_waitcnt lgkmcnt(0)
	v_add_f32_e32 v100, v100, v101
	v_mov_b32_e32 v101, v100
	s_nop 1
	v_permlane32_swap_b32_e32 v100, v101
	v_add_f32_e32 v108, v100, v101
	s_nop 0
	v_lshl_add_u64 v[98:99], v[144:145], 0, v[114:115]
	v_mov_b32_e32 v96, v108
	v_fmamk_f32 v96, v96, 0x3a800000, v154
	v_mul_f32_e32 v97, 0x4b800000, v96
	v_cmp_gt_f32_e32 vcc, s48, v96
	s_nop 1
	v_cndmask_b32_e32 v96, v96, v97, vcc
	v_rsq_f32_e32 v100, v96
	v_lshlrev_b64 v[96:97], 6, v[112:113]
	v_lshl_add_u64 v[96:97], s[10:11], 0, v[96:97]
	v_mul_f32_e32 v101, 0x45800000, v100
	v_cndmask_b32_e32 v100, v100, v101, vcc
	v_pk_mul_f32 v[94:95], v[94:95], v[100:101] op_sel_hi:[1,0]
	v_pk_mul_f32 v[92:93], v[92:93], v[100:101] op_sel_hi:[1,0]
	v_pk_mul_f32 v[90:91], v[90:91], v[100:101] op_sel_hi:[1,0]
	v_pk_mul_f32 v[88:89], v[88:89], v[100:101] op_sel_hi:[1,0]
	v_pk_mul_f32 v[82:83], v[82:83], v[100:101] op_sel_hi:[1,0]
	v_pk_mul_f32 v[80:81], v[80:81], v[100:101] op_sel_hi:[1,0]
	v_pk_mul_f32 v[86:87], v[86:87], v[100:101] op_sel_hi:[1,0]
	v_pk_mul_f32 v[84:85], v[84:85], v[100:101] op_sel_hi:[1,0]
	v_max_f32_e32 v92, 0, v92
	v_max_f32_e32 v88, 0, v88
	v_max_f32_e32 v93, 0, v93
	v_max_f32_e32 v89, 0, v89
	v_max_f32_e32 v94, 0, v94
	v_max_f32_e32 v90, 0, v90
	v_max_f32_e32 v95, 0, v95
	v_max_f32_e32 v91, 0, v91
	v_max_f32_e32 v80, 0, v80
	v_max_f32_e32 v81, 0, v81
	v_max_f32_e32 v82, 0, v82
	v_max_f32_e32 v83, 0, v83
	v_max_f32_e32 v84, 0, v84
	v_max_f32_e32 v85, 0, v85
	v_max_f32_e32 v86, 0, v86
	v_max_f32_e32 v87, 0, v87
	v_mul_f32_e32 v92, v92, v92
	v_mul_f32_e32 v88, v88, v88
	v_mul_f32_e32 v93, v93, v93
	v_mul_f32_e32 v89, v89, v89
	v_mul_f32_e32 v94, v94, v94
	v_mul_f32_e32 v90, v90, v90
	v_mul_f32_e32 v95, v95, v95
	v_mul_f32_e32 v91, v91, v91
	v_mul_f32_e32 v100, v80, v80
	v_mul_f32_e32 v101, v81, v81
	v_mul_f32_e32 v102, v82, v82
	v_mul_f32_e32 v103, v83, v83
	v_cvt_pk_bf16_f32 v80, v92, v93
	v_cvt_pk_bf16_f32 v81, v94, v95
	v_cvt_pk_bf16_f32 v82, v88, v89
	v_cvt_pk_bf16_f32 v83, v90, v91
	v_mul_f32_e32 v84, v84, v84
	v_mul_f32_e32 v85, v85, v85
	v_mul_f32_e32 v86, v86, v86
	v_mul_f32_e32 v87, v87, v87
	global_store_dwordx4 v[98:99], v[80:83], off
	s_nop 1
	v_cvt_pk_bf16_f32 v80, v84, v85
	v_cvt_pk_bf16_f32 v81, v86, v87
	v_cvt_pk_bf16_f32 v82, v100, v101
	v_cvt_pk_bf16_f32 v83, v102, v103
	global_store_dwordx4 v[98:99], v[80:83], off offset:256
	s_nop 0
	v_add_u32_e32 v96, 0x80, v146
	v_ashrrev_i32_e32 v97, 31, v96
	v_lshlrev_b64 v[98:99], 13, v[112:113]
	s_waitcnt vmcnt(10)
	v_add_f32_e32 v84, v188, v189
	v_add_f32_e32 v85, v190, v191
	v_add_f32_e32 v84, v84, v85
	ds_swizzle_b32 v85, v84 offset:swizzle(SWAP,16)
	s_waitcnt lgkmcnt(0)
	v_add_f32_e32 v84, v84, v85
	v_mov_b32_e32 v85, v84
	s_nop 1
	v_permlane32_swap_b32_e32 v84, v85
	v_add_f32_e32 v92, v84, v85
	s_nop 0
	v_lshl_add_u64 v[82:83], v[144:145], 0, v[98:99]
	v_mov_b32_e32 v80, v92
	v_fmamk_f32 v80, v80, 0x3a800000, v154
	v_mul_f32_e32 v81, 0x4b800000, v80
	v_cmp_gt_f32_e32 vcc, s48, v80
	s_nop 1
	v_cndmask_b32_e32 v80, v80, v81, vcc
	v_rsq_f32_e32 v84, v80
	v_lshlrev_b64 v[80:81], 6, v[96:97]
	v_lshl_add_u64 v[80:81], s[10:11], 0, v[80:81]
	v_mul_f32_e32 v85, 0x45800000, v84
	v_cndmask_b32_e32 v84, v84, v85, vcc
	v_pk_mul_f32 v[78:79], v[78:79], v[84:85] op_sel_hi:[1,0]
	v_pk_mul_f32 v[76:77], v[76:77], v[84:85] op_sel_hi:[1,0]
	v_pk_mul_f32 v[74:75], v[74:75], v[84:85] op_sel_hi:[1,0]
	v_pk_mul_f32 v[72:73], v[72:73], v[84:85] op_sel_hi:[1,0]
	v_pk_mul_f32 v[66:67], v[66:67], v[84:85] op_sel_hi:[1,0]
	v_pk_mul_f32 v[64:65], v[64:65], v[84:85] op_sel_hi:[1,0]
	v_pk_mul_f32 v[70:71], v[70:71], v[84:85] op_sel_hi:[1,0]
	v_pk_mul_f32 v[68:69], v[68:69], v[84:85] op_sel_hi:[1,0]
	v_max_f32_e32 v76, 0, v76
	v_max_f32_e32 v72, 0, v72
	v_max_f32_e32 v77, 0, v77
	v_max_f32_e32 v73, 0, v73
	v_max_f32_e32 v78, 0, v78
	v_max_f32_e32 v74, 0, v74
	v_max_f32_e32 v79, 0, v79
	v_max_f32_e32 v75, 0, v75
	v_max_f32_e32 v64, 0, v64
	v_max_f32_e32 v65, 0, v65
	v_max_f32_e32 v66, 0, v66
	v_max_f32_e32 v67, 0, v67
	v_max_f32_e32 v68, 0, v68
	v_max_f32_e32 v69, 0, v69
	v_max_f32_e32 v70, 0, v70
	v_max_f32_e32 v71, 0, v71
	v_mul_f32_e32 v76, v76, v76
	v_mul_f32_e32 v72, v72, v72
	v_mul_f32_e32 v77, v77, v77
	v_mul_f32_e32 v73, v73, v73
	v_mul_f32_e32 v78, v78, v78
	v_mul_f32_e32 v74, v74, v74
	v_mul_f32_e32 v79, v79, v79
	v_mul_f32_e32 v75, v75, v75
	v_mul_f32_e32 v84, v64, v64
	v_mul_f32_e32 v85, v65, v65
	v_mul_f32_e32 v86, v66, v66
	v_mul_f32_e32 v87, v67, v67
	v_cvt_pk_bf16_f32 v64, v76, v77
	v_cvt_pk_bf16_f32 v65, v78, v79
	v_cvt_pk_bf16_f32 v66, v72, v73
	v_cvt_pk_bf16_f32 v67, v74, v75
	v_mul_f32_e32 v68, v68, v68
	v_mul_f32_e32 v69, v69, v69
	v_mul_f32_e32 v70, v70, v70
	v_mul_f32_e32 v71, v71, v71
	global_store_dwordx4 v[82:83], v[64:67], off
	s_nop 1
	v_cvt_pk_bf16_f32 v64, v68, v69
	v_cvt_pk_bf16_f32 v65, v70, v71
	v_cvt_pk_bf16_f32 v66, v84, v85
	v_cvt_pk_bf16_f32 v67, v86, v87
	global_store_dwordx4 v[82:83], v[64:67], off offset:256
	s_nop 0
	v_add_u32_e32 v80, 0x90, v146
	v_ashrrev_i32_e32 v81, 31, v80
	v_lshlrev_b64 v[82:83], 13, v[96:97]
	s_waitcnt vmcnt(11)
	v_add_f32_e32 v68, v192, v193
	v_add_f32_e32 v69, v194, v195
	v_add_f32_e32 v68, v68, v69
	ds_swizzle_b32 v69, v68 offset:swizzle(SWAP,16)
	s_waitcnt lgkmcnt(0)
	v_add_f32_e32 v68, v68, v69
	v_mov_b32_e32 v69, v68
	s_nop 1
	v_permlane32_swap_b32_e32 v68, v69
	v_add_f32_e32 v76, v68, v69
	s_nop 0
	v_lshl_add_u64 v[66:67], v[144:145], 0, v[82:83]
	v_mov_b32_e32 v64, v76
	v_fmamk_f32 v64, v64, 0x3a800000, v154
	v_mul_f32_e32 v65, 0x4b800000, v64
	v_cmp_gt_f32_e32 vcc, s48, v64
	s_nop 1
	v_cndmask_b32_e32 v64, v64, v65, vcc
	v_rsq_f32_e32 v68, v64
	v_lshlrev_b64 v[64:65], 6, v[80:81]
	v_lshl_add_u64 v[64:65], s[10:11], 0, v[64:65]
	v_mul_f32_e32 v69, 0x45800000, v68
	v_cndmask_b32_e32 v68, v68, v69, vcc
	v_pk_mul_f32 v[62:63], v[62:63], v[68:69] op_sel_hi:[1,0]
	v_pk_mul_f32 v[60:61], v[60:61], v[68:69] op_sel_hi:[1,0]
	v_pk_mul_f32 v[58:59], v[58:59], v[68:69] op_sel_hi:[1,0]
	v_pk_mul_f32 v[56:57], v[56:57], v[68:69] op_sel_hi:[1,0]
	v_pk_mul_f32 v[50:51], v[50:51], v[68:69] op_sel_hi:[1,0]
	v_pk_mul_f32 v[48:49], v[48:49], v[68:69] op_sel_hi:[1,0]
	v_pk_mul_f32 v[54:55], v[54:55], v[68:69] op_sel_hi:[1,0]
	v_pk_mul_f32 v[52:53], v[52:53], v[68:69] op_sel_hi:[1,0]
	v_max_f32_e32 v60, 0, v60
	v_max_f32_e32 v56, 0, v56
	v_max_f32_e32 v61, 0, v61
	v_max_f32_e32 v57, 0, v57
	v_max_f32_e32 v62, 0, v62
	v_max_f32_e32 v58, 0, v58
	v_max_f32_e32 v63, 0, v63
	v_max_f32_e32 v59, 0, v59
	v_max_f32_e32 v48, 0, v48
	v_max_f32_e32 v49, 0, v49
	v_max_f32_e32 v50, 0, v50
	v_max_f32_e32 v51, 0, v51
	v_max_f32_e32 v52, 0, v52
	v_max_f32_e32 v53, 0, v53
	v_max_f32_e32 v54, 0, v54
	v_max_f32_e32 v55, 0, v55
	v_mul_f32_e32 v60, v60, v60
	v_mul_f32_e32 v56, v56, v56
	v_mul_f32_e32 v61, v61, v61
	v_mul_f32_e32 v57, v57, v57
	v_mul_f32_e32 v62, v62, v62
	v_mul_f32_e32 v58, v58, v58
	v_mul_f32_e32 v63, v63, v63
	v_mul_f32_e32 v59, v59, v59
	v_mul_f32_e32 v68, v48, v48
	v_mul_f32_e32 v69, v49, v49
	v_mul_f32_e32 v70, v50, v50
	v_mul_f32_e32 v71, v51, v51
	v_cvt_pk_bf16_f32 v48, v60, v61
	v_cvt_pk_bf16_f32 v49, v62, v63
	v_cvt_pk_bf16_f32 v50, v56, v57
	v_cvt_pk_bf16_f32 v51, v58, v59
	v_mul_f32_e32 v52, v52, v52
	v_mul_f32_e32 v53, v53, v53
	v_mul_f32_e32 v54, v54, v54
	v_mul_f32_e32 v55, v55, v55
	global_store_dwordx4 v[66:67], v[48:51], off
	s_nop 1
	v_cvt_pk_bf16_f32 v48, v52, v53
	v_cvt_pk_bf16_f32 v49, v54, v55
	v_cvt_pk_bf16_f32 v50, v68, v69
	v_cvt_pk_bf16_f32 v51, v70, v71
	global_store_dwordx4 v[66:67], v[48:51], off offset:256
	s_nop 0
	v_add_u32_e32 v64, 0xa0, v146
	v_ashrrev_i32_e32 v65, 31, v64
	v_lshlrev_b64 v[66:67], 13, v[80:81]
	s_waitcnt vmcnt(12)
	v_add_f32_e32 v52, v196, v197
	v_add_f32_e32 v53, v198, v199
	v_add_f32_e32 v52, v52, v53
	ds_swizzle_b32 v53, v52 offset:swizzle(SWAP,16)
	s_waitcnt lgkmcnt(0)
	v_add_f32_e32 v52, v52, v53
	v_mov_b32_e32 v53, v52
	s_nop 1
	v_permlane32_swap_b32_e32 v52, v53
	v_add_f32_e32 v60, v52, v53
	s_nop 0
	v_lshl_add_u64 v[50:51], v[144:145], 0, v[66:67]
	v_mov_b32_e32 v48, v60
	v_fmamk_f32 v48, v48, 0x3a800000, v154
	v_mul_f32_e32 v49, 0x4b800000, v48
	v_cmp_gt_f32_e32 vcc, s48, v48
	s_nop 1
	v_cndmask_b32_e32 v48, v48, v49, vcc
	v_rsq_f32_e32 v52, v48
	v_lshlrev_b64 v[48:49], 6, v[64:65]
	v_lshl_add_u64 v[48:49], s[10:11], 0, v[48:49]
	v_mul_f32_e32 v53, 0x45800000, v52
	v_cndmask_b32_e32 v52, v52, v53, vcc
	v_pk_mul_f32 v[46:47], v[46:47], v[52:53] op_sel_hi:[1,0]
	v_pk_mul_f32 v[44:45], v[44:45], v[52:53] op_sel_hi:[1,0]
	v_pk_mul_f32 v[42:43], v[42:43], v[52:53] op_sel_hi:[1,0]
	v_pk_mul_f32 v[40:41], v[40:41], v[52:53] op_sel_hi:[1,0]
	v_pk_mul_f32 v[34:35], v[34:35], v[52:53] op_sel_hi:[1,0]
	v_pk_mul_f32 v[32:33], v[32:33], v[52:53] op_sel_hi:[1,0]
	v_pk_mul_f32 v[38:39], v[38:39], v[52:53] op_sel_hi:[1,0]
	v_pk_mul_f32 v[36:37], v[36:37], v[52:53] op_sel_hi:[1,0]
	v_max_f32_e32 v44, 0, v44
	v_max_f32_e32 v40, 0, v40
	v_max_f32_e32 v45, 0, v45
	v_max_f32_e32 v41, 0, v41
	v_max_f32_e32 v46, 0, v46
	v_max_f32_e32 v42, 0, v42
	v_max_f32_e32 v47, 0, v47
	v_max_f32_e32 v43, 0, v43
	v_max_f32_e32 v32, 0, v32
	v_max_f32_e32 v33, 0, v33
	v_max_f32_e32 v34, 0, v34
	v_max_f32_e32 v35, 0, v35
	v_max_f32_e32 v36, 0, v36
	v_max_f32_e32 v37, 0, v37
	v_max_f32_e32 v38, 0, v38
	v_max_f32_e32 v39, 0, v39
	v_mul_f32_e32 v44, v44, v44
	v_mul_f32_e32 v40, v40, v40
	v_mul_f32_e32 v45, v45, v45
	v_mul_f32_e32 v41, v41, v41
	v_mul_f32_e32 v46, v46, v46
	v_mul_f32_e32 v42, v42, v42
	v_mul_f32_e32 v47, v47, v47
	v_mul_f32_e32 v43, v43, v43
	v_mul_f32_e32 v52, v32, v32
	v_mul_f32_e32 v53, v33, v33
	v_mul_f32_e32 v54, v34, v34
	v_mul_f32_e32 v55, v35, v35
	v_cvt_pk_bf16_f32 v32, v44, v45
	v_cvt_pk_bf16_f32 v33, v46, v47
	v_cvt_pk_bf16_f32 v34, v40, v41
	v_cvt_pk_bf16_f32 v35, v42, v43
	v_mul_f32_e32 v36, v36, v36
	v_mul_f32_e32 v37, v37, v37
	v_mul_f32_e32 v38, v38, v38
	v_mul_f32_e32 v39, v39, v39
	global_store_dwordx4 v[50:51], v[32:35], off
	s_nop 1
	v_cvt_pk_bf16_f32 v32, v36, v37
	v_cvt_pk_bf16_f32 v33, v38, v39
	v_cvt_pk_bf16_f32 v34, v52, v53
	v_cvt_pk_bf16_f32 v35, v54, v55
	global_store_dwordx4 v[50:51], v[32:35], off offset:256
	s_nop 0
	v_add_u32_e32 v48, 0xb0, v146
	v_ashrrev_i32_e32 v49, 31, v48
	v_lshlrev_b64 v[50:51], 13, v[64:65]
	s_waitcnt vmcnt(13)
	v_add_f32_e32 v36, v200, v201
	v_add_f32_e32 v37, v202, v203
	v_add_f32_e32 v36, v36, v37
	ds_swizzle_b32 v37, v36 offset:swizzle(SWAP,16)
	s_waitcnt lgkmcnt(0)
	v_add_f32_e32 v36, v36, v37
	v_mov_b32_e32 v37, v36
	s_nop 1
	v_permlane32_swap_b32_e32 v36, v37
	v_add_f32_e32 v44, v36, v37
	s_nop 0
	v_lshl_add_u64 v[34:35], v[144:145], 0, v[50:51]
	v_mov_b32_e32 v32, v44
	v_fmamk_f32 v32, v32, 0x3a800000, v154
	v_mul_f32_e32 v33, 0x4b800000, v32
	v_cmp_gt_f32_e32 vcc, s48, v32
	s_nop 1
	v_cndmask_b32_e32 v32, v32, v33, vcc
	v_rsq_f32_e32 v36, v32
	v_lshlrev_b64 v[32:33], 6, v[48:49]
	v_lshl_add_u64 v[32:33], s[10:11], 0, v[32:33]
	v_mul_f32_e32 v37, 0x45800000, v36
	v_cndmask_b32_e32 v36, v36, v37, vcc
	v_pk_mul_f32 v[30:31], v[30:31], v[36:37] op_sel_hi:[1,0]
	v_pk_mul_f32 v[28:29], v[28:29], v[36:37] op_sel_hi:[1,0]
	v_pk_mul_f32 v[26:27], v[26:27], v[36:37] op_sel_hi:[1,0]
	v_pk_mul_f32 v[24:25], v[24:25], v[36:37] op_sel_hi:[1,0]
	v_pk_mul_f32 v[18:19], v[18:19], v[36:37] op_sel_hi:[1,0]
	v_pk_mul_f32 v[16:17], v[16:17], v[36:37] op_sel_hi:[1,0]
	v_pk_mul_f32 v[22:23], v[22:23], v[36:37] op_sel_hi:[1,0]
	v_pk_mul_f32 v[20:21], v[20:21], v[36:37] op_sel_hi:[1,0]
	v_max_f32_e32 v28, 0, v28
	v_max_f32_e32 v24, 0, v24
	v_max_f32_e32 v29, 0, v29
	v_max_f32_e32 v25, 0, v25
	v_max_f32_e32 v30, 0, v30
	v_max_f32_e32 v26, 0, v26
	v_max_f32_e32 v31, 0, v31
	v_max_f32_e32 v27, 0, v27
	v_max_f32_e32 v16, 0, v16
	v_max_f32_e32 v17, 0, v17
	v_max_f32_e32 v18, 0, v18
	v_max_f32_e32 v19, 0, v19
	v_max_f32_e32 v20, 0, v20
	v_max_f32_e32 v21, 0, v21
	v_max_f32_e32 v22, 0, v22
	v_max_f32_e32 v23, 0, v23
	v_mul_f32_e32 v28, v28, v28
	v_mul_f32_e32 v24, v24, v24
	v_mul_f32_e32 v29, v29, v29
	v_mul_f32_e32 v25, v25, v25
	v_mul_f32_e32 v30, v30, v30
	v_mul_f32_e32 v26, v26, v26
	v_mul_f32_e32 v31, v31, v31
	v_mul_f32_e32 v27, v27, v27
	v_mul_f32_e32 v36, v16, v16
	v_mul_f32_e32 v37, v17, v17
	v_mul_f32_e32 v38, v18, v18
	v_mul_f32_e32 v39, v19, v19
	v_cvt_pk_bf16_f32 v16, v28, v29
	v_cvt_pk_bf16_f32 v17, v30, v31
	v_cvt_pk_bf16_f32 v18, v24, v25
	v_cvt_pk_bf16_f32 v19, v26, v27
	v_mul_f32_e32 v20, v20, v20
	v_mul_f32_e32 v21, v21, v21
	v_mul_f32_e32 v22, v22, v22
	v_mul_f32_e32 v23, v23, v23
	global_store_dwordx4 v[34:35], v[16:19], off
	s_andn2_b64 vcc, exec, s[4:5]
	s_mov_b64 s[4:5], -1
	v_cvt_pk_bf16_f32 v16, v20, v21
	v_cvt_pk_bf16_f32 v17, v22, v23
	v_cvt_pk_bf16_f32 v18, v36, v37
	v_cvt_pk_bf16_f32 v19, v38, v39
	global_store_dwordx4 v[34:35], v[16:19], off offset:256
	s_nop 0
	s_waitcnt vmcnt(14)
	v_add_f32_e32 v20, v208, v209
	v_add_f32_e32 v21, v210, v211
	v_add_f32_e32 v20, v20, v21
	ds_swizzle_b32 v21, v20 offset:swizzle(SWAP,16)
	s_waitcnt lgkmcnt(0)
	v_add_f32_e32 v20, v20, v21
	v_mov_b32_e32 v21, v20
	s_nop 1
	v_permlane32_swap_b32_e32 v20, v21
	v_add_f32_e32 v28, v20, v21
	s_nop 0
	s_nop 0
	v_mov_b32_e32 v16, v28
	v_fmamk_f32 v16, v16, 0x3a800000, v154
	v_mul_f32_e32 v17, 0x4b800000, v16
	v_cmp_gt_f32_e64 s[6:7], s48, v16
	s_nop 1
	v_cndmask_b32_e64 v16, v16, v17, s[6:7]
	v_rsq_f32_e32 v18, v16
	v_lshlrev_b64 v[16:17], 13, v[48:49]
	v_lshl_add_u64 v[16:17], v[144:145], 0, v[16:17]
	v_mul_f32_e32 v19, 0x45800000, v18
	v_cndmask_b32_e64 v18, v18, v19, s[6:7]
	v_pk_mul_f32 v[14:15], v[14:15], v[18:19] op_sel_hi:[1,0]
	v_pk_mul_f32 v[12:13], v[12:13], v[18:19] op_sel_hi:[1,0]
	v_pk_mul_f32 v[10:11], v[10:11], v[18:19] op_sel_hi:[1,0]
	v_pk_mul_f32 v[8:9], v[8:9], v[18:19] op_sel_hi:[1,0]
	v_pk_mul_f32 v[2:3], v[2:3], v[18:19] op_sel_hi:[1,0]
	v_pk_mul_f32 v[0:1], v[0:1], v[18:19] op_sel_hi:[1,0]
	v_pk_mul_f32 v[6:7], v[6:7], v[18:19] op_sel_hi:[1,0]
	v_pk_mul_f32 v[4:5], v[4:5], v[18:19] op_sel_hi:[1,0]
	v_max_f32_e32 v12, 0, v12
	v_max_f32_e32 v8, 0, v8
	v_max_f32_e32 v13, 0, v13
	v_max_f32_e32 v9, 0, v9
	v_max_f32_e32 v14, 0, v14
	v_max_f32_e32 v10, 0, v10
	v_max_f32_e32 v15, 0, v15
	v_max_f32_e32 v11, 0, v11
	v_max_f32_e32 v0, 0, v0
	v_max_f32_e32 v1, 0, v1
	v_max_f32_e32 v2, 0, v2
	v_max_f32_e32 v3, 0, v3
	v_max_f32_e32 v4, 0, v4
	v_max_f32_e32 v5, 0, v5
	v_max_f32_e32 v6, 0, v6
	v_max_f32_e32 v7, 0, v7
	v_mul_f32_e32 v12, v12, v12
	v_mul_f32_e32 v8, v8, v8
	v_mul_f32_e32 v13, v13, v13
	v_mul_f32_e32 v9, v9, v9
	v_mul_f32_e32 v14, v14, v14
	v_mul_f32_e32 v10, v10, v10
	v_mul_f32_e32 v15, v15, v15
	v_mul_f32_e32 v11, v11, v11
	v_mul_f32_e32 v18, v0, v0
	v_mul_f32_e32 v19, v1, v1
	v_mul_f32_e32 v20, v2, v2
	v_mul_f32_e32 v21, v3, v3
	v_cvt_pk_bf16_f32 v0, v12, v13
	v_cvt_pk_bf16_f32 v1, v14, v15
	v_cvt_pk_bf16_f32 v2, v8, v9
	v_cvt_pk_bf16_f32 v3, v10, v11
	v_mul_f32_e32 v4, v4, v4
	v_mul_f32_e32 v5, v5, v5
	v_mul_f32_e32 v6, v6, v6
	v_mul_f32_e32 v7, v7, v7
	global_store_dwordx4 v[16:17], v[0:3], off
	s_nop 1
	v_cvt_pk_bf16_f32 v0, v4, v5
	v_cvt_pk_bf16_f32 v1, v6, v7
	v_cvt_pk_bf16_f32 v2, v18, v19
	v_cvt_pk_bf16_f32 v3, v20, v21
	global_store_dwordx4 v[16:17], v[0:3], off offset:256
	s_cbranch_vccnz .LBB0_2171
	s_andn2_b64 vcc, exec, s[2:3]
	s_cbranch_vccnz .LBB0_2170
	s_barrier
	s_branch .LBB0_2170

.LBB0_2848:
	v_lshl_add_u32 v146, s6, 8, v148
	v_ashrrev_i32_e32 v147, 31, v146
	v_lshlrev_b64 v[144:145], 6, v[146:147]
	v_lshl_add_u64 v[144:145], s[10:11], 0, v[144:145]
	v_bfe_u32 v164, v206, 4, 2
	v_lshlrev_b32_e32 v164, 4, v164
	v_mov_b32_e32 v165, 0
	v_lshl_add_u64 v[160:161], v[144:145], 0, v[164:165]
	global_load_dwordx4 v[176:179], v[160:161], off
	global_load_dwordx4 v[180:183], v[160:161], off offset:1024
	global_load_dwordx4 v[184:187], v[160:161], off offset:2048
	global_load_dwordx4 v[188:191], v[160:161], off offset:3072
	s_mov_b64 s[100:101], 0x2000
	v_lshl_add_u64 v[212:213], v[160:161], 0, s[100:101]
	global_load_dwordx4 v[192:195], v[212:213], off
	global_load_dwordx4 v[196:199], v[212:213], off offset:1024
	global_load_dwordx4 v[200:203], v[212:213], off offset:2048
	global_load_dwordx4 v[208:211], v[212:213], off offset:3072
	v_lshlrev_b64 v[174:175], 13, v[146:147]
	v_lshl_or_b32 v144, s7, 8, v150
	v_ashrrev_i32_e32 v145, 31, v144
	v_or_b32_e32 v172, 16, v146
	v_lshl_add_u64 v[144:145], v[144:145], 1, s[8:9]
	v_ashrrev_i32_e32 v173, 31, v172
	s_waitcnt vmcnt(7)
	v_add_f32_e32 v160, v176, v177
	v_add_f32_e32 v161, v178, v179
	v_add_f32_e32 v160, v160, v161
	ds_swizzle_b32 v161, v160 offset:swizzle(SWAP,16)
	s_waitcnt lgkmcnt(0)
	v_add_f32_e32 v160, v160, v161
	v_mov_b32_e32 v161, v160
	s_nop 1
	v_permlane32_swap_b32_e32 v160, v161
	v_add_f32_e32 v168, v160, v161
	s_nop 0
	v_lshlrev_b64 v[158:159], 6, v[172:173]
	v_mov_b32_e32 v147, v168
	v_fmamk_f32 v147, v147, 0x3a800000, v154
	v_mul_f32_e32 v155, 0x4b800000, v147
	v_cmp_gt_f32_e32 vcc, s48, v147
	v_lshl_add_u64 v[156:157], v[144:145], 0, v[174:175]
	v_lshl_add_u64 v[158:159], s[10:11], 0, v[158:159]
	v_cndmask_b32_e32 v147, v147, v155, vcc
	v_rsq_f32_e32 v147, v147
	s_nop 0
	v_mul_f32_e32 v155, 0x45800000, v147
	v_cndmask_b32_e32 v160, v147, v155, vcc
	v_pk_mul_f32 v[126:127], v[126:127], v[160:161] op_sel_hi:[1,0]
	v_pk_mul_f32 v[124:125], v[124:125], v[160:161] op_sel_hi:[1,0]
	v_pk_mul_f32 v[122:123], v[122:123], v[160:161] op_sel_hi:[1,0]
	v_pk_mul_f32 v[120:121], v[120:121], v[160:161] op_sel_hi:[1,0]
	v_pk_mul_f32 v[114:115], v[114:115], v[160:161] op_sel_hi:[1,0]
	v_pk_mul_f32 v[112:113], v[112:113], v[160:161] op_sel_hi:[1,0]
	v_pk_mul_f32 v[118:119], v[118:119], v[160:161] op_sel_hi:[1,0]
	v_pk_mul_f32 v[116:117], v[116:117], v[160:161] op_sel_hi:[1,0]
	v_max_f32_e32 v124, 0, v124
	v_max_f32_e32 v120, 0, v120
	v_max_f32_e32 v125, 0, v125
	v_max_f32_e32 v121, 0, v121
	v_max_f32_e32 v126, 0, v126
	v_max_f32_e32 v122, 0, v122
	v_max_f32_e32 v127, 0, v127
	v_max_f32_e32 v123, 0, v123
	v_max_f32_e32 v112, 0, v112
	v_max_f32_e32 v113, 0, v113
	v_max_f32_e32 v114, 0, v114
	v_max_f32_e32 v115, 0, v115
	v_max_f32_e32 v116, 0, v116
	v_max_f32_e32 v117, 0, v117
	v_max_f32_e32 v118, 0, v118
	v_max_f32_e32 v119, 0, v119
	v_mul_f32_e32 v124, v124, v124
	v_mul_f32_e32 v120, v120, v120
	v_mul_f32_e32 v125, v125, v125
	v_mul_f32_e32 v121, v121, v121
	v_mul_f32_e32 v126, v126, v126
	v_mul_f32_e32 v122, v122, v122
	v_mul_f32_e32 v127, v127, v127
	v_mul_f32_e32 v123, v123, v123
	v_mul_f32_e32 v147, v112, v112
	v_mul_f32_e32 v155, v113, v113
	v_mul_f32_e32 v160, v114, v114
	v_mul_f32_e32 v161, v115, v115
	v_cvt_pk_bf16_f32 v112, v124, v125
	v_cvt_pk_bf16_f32 v113, v126, v127
	v_cvt_pk_bf16_f32 v114, v120, v121
	v_cvt_pk_bf16_f32 v115, v122, v123
	v_mul_f32_e32 v116, v116, v116
	v_mul_f32_e32 v117, v117, v117
	v_mul_f32_e32 v118, v118, v118
	v_mul_f32_e32 v119, v119, v119
	global_store_dwordx4 v[156:157], v[112:115], off
	s_nop 1
	v_cvt_pk_bf16_f32 v112, v116, v117
	v_cvt_pk_bf16_f32 v113, v118, v119
	v_cvt_pk_bf16_f32 v114, v147, v155
	v_cvt_pk_bf16_f32 v115, v160, v161
	global_store_dwordx4 v[156:157], v[112:115], off offset:256
	s_nop 0
	v_or_b32_e32 v156, 32, v146
	v_ashrrev_i32_e32 v157, 31, v156
	v_lshlrev_b64 v[158:159], 13, v[172:173]
	s_waitcnt vmcnt(8)
	v_add_f32_e32 v116, v180, v181
	v_add_f32_e32 v117, v182, v183
	v_add_f32_e32 v116, v116, v117
	ds_swizzle_b32 v117, v116 offset:swizzle(SWAP,16)
	s_waitcnt lgkmcnt(0)
	v_add_f32_e32 v116, v116, v117
	v_mov_b32_e32 v117, v116
	s_nop 1
	v_permlane32_swap_b32_e32 v116, v117
	v_add_f32_e32 v124, v116, v117
	s_nop 0
	v_lshl_add_u64 v[114:115], v[144:145], 0, v[158:159]
	v_mov_b32_e32 v112, v124
	v_fmamk_f32 v112, v112, 0x3a800000, v154
	v_mul_f32_e32 v113, 0x4b800000, v112
	v_cmp_gt_f32_e32 vcc, s48, v112
	s_nop 1
	v_cndmask_b32_e32 v112, v112, v113, vcc
	v_rsq_f32_e32 v116, v112
	v_lshlrev_b64 v[112:113], 6, v[156:157]
	v_lshl_add_u64 v[112:113], s[10:11], 0, v[112:113]
	v_mul_f32_e32 v117, 0x45800000, v116
	v_cndmask_b32_e32 v116, v116, v117, vcc
	v_pk_mul_f32 v[110:111], v[110:111], v[116:117] op_sel_hi:[1,0]
	v_pk_mul_f32 v[108:109], v[108:109], v[116:117] op_sel_hi:[1,0]
	v_pk_mul_f32 v[106:107], v[106:107], v[116:117] op_sel_hi:[1,0]
	v_pk_mul_f32 v[104:105], v[104:105], v[116:117] op_sel_hi:[1,0]
	v_pk_mul_f32 v[98:99], v[98:99], v[116:117] op_sel_hi:[1,0]
	v_pk_mul_f32 v[96:97], v[96:97], v[116:117] op_sel_hi:[1,0]
	v_pk_mul_f32 v[102:103], v[102:103], v[116:117] op_sel_hi:[1,0]
	v_pk_mul_f32 v[100:101], v[100:101], v[116:117] op_sel_hi:[1,0]
	v_max_f32_e32 v108, 0, v108
	v_max_f32_e32 v104, 0, v104
	v_max_f32_e32 v109, 0, v109
	v_max_f32_e32 v105, 0, v105
	v_max_f32_e32 v110, 0, v110
	v_max_f32_e32 v106, 0, v106
	v_max_f32_e32 v111, 0, v111
	v_max_f32_e32 v107, 0, v107
	v_max_f32_e32 v96, 0, v96
	v_max_f32_e32 v97, 0, v97
	v_max_f32_e32 v98, 0, v98
	v_max_f32_e32 v99, 0, v99
	v_max_f32_e32 v100, 0, v100
	v_max_f32_e32 v101, 0, v101
	v_max_f32_e32 v102, 0, v102
	v_max_f32_e32 v103, 0, v103
	v_mul_f32_e32 v108, v108, v108
	v_mul_f32_e32 v104, v104, v104
	v_mul_f32_e32 v109, v109, v109
	v_mul_f32_e32 v105, v105, v105
	v_mul_f32_e32 v110, v110, v110
	v_mul_f32_e32 v106, v106, v106
	v_mul_f32_e32 v111, v111, v111
	v_mul_f32_e32 v107, v107, v107
	v_mul_f32_e32 v116, v96, v96
	v_mul_f32_e32 v117, v97, v97
	v_mul_f32_e32 v118, v98, v98
	v_mul_f32_e32 v119, v99, v99
	v_cvt_pk_bf16_f32 v96, v108, v109
	v_cvt_pk_bf16_f32 v97, v110, v111
	v_cvt_pk_bf16_f32 v98, v104, v105
	v_cvt_pk_bf16_f32 v99, v106, v107
	v_mul_f32_e32 v100, v100, v100
	v_mul_f32_e32 v101, v101, v101
	v_mul_f32_e32 v102, v102, v102
	v_mul_f32_e32 v103, v103, v103
	global_store_dwordx4 v[114:115], v[96:99], off
	s_nop 1
	v_cvt_pk_bf16_f32 v96, v100, v101
	v_cvt_pk_bf16_f32 v97, v102, v103
	v_cvt_pk_bf16_f32 v98, v116, v117
	v_cvt_pk_bf16_f32 v99, v118, v119
	global_store_dwordx4 v[114:115], v[96:99], off offset:256
	s_nop 0
	v_or_b32_e32 v112, 48, v146
	v_ashrrev_i32_e32 v113, 31, v112
	v_lshlrev_b64 v[114:115], 13, v[156:157]
	s_waitcnt vmcnt(9)
	v_add_f32_e32 v100, v184, v185
	v_add_f32_e32 v101, v186, v187
	v_add_f32_e32 v100, v100, v101
	ds_swizzle_b32 v101, v100 offset:swizzle(SWAP,16)
	s_waitcnt lgkmcnt(0)
	v_add_f32_e32 v100, v100, v101
	v_mov_b32_e32 v101, v100
	s_nop 1
	v_permlane32_swap_b32_e32 v100, v101
	v_add_f32_e32 v108, v100, v101
	s_nop 0
	v_lshl_add_u64 v[98:99], v[144:145], 0, v[114:115]
	v_mov_b32_e32 v96, v108
	v_fmamk_f32 v96, v96, 0x3a800000, v154
	v_mul_f32_e32 v97, 0x4b800000, v96
	v_cmp_gt_f32_e32 vcc, s48, v96
	s_nop 1
	v_cndmask_b32_e32 v96, v96, v97, vcc
	v_rsq_f32_e32 v100, v96
	v_lshlrev_b64 v[96:97], 6, v[112:113]
	v_lshl_add_u64 v[96:97], s[10:11], 0, v[96:97]
	v_mul_f32_e32 v101, 0x45800000, v100
	v_cndmask_b32_e32 v100, v100, v101, vcc
	v_pk_mul_f32 v[94:95], v[94:95], v[100:101] op_sel_hi:[1,0]
	v_pk_mul_f32 v[92:93], v[92:93], v[100:101] op_sel_hi:[1,0]
	v_pk_mul_f32 v[90:91], v[90:91], v[100:101] op_sel_hi:[1,0]
	v_pk_mul_f32 v[88:89], v[88:89], v[100:101] op_sel_hi:[1,0]
	v_pk_mul_f32 v[82:83], v[82:83], v[100:101] op_sel_hi:[1,0]
	v_pk_mul_f32 v[80:81], v[80:81], v[100:101] op_sel_hi:[1,0]
	v_pk_mul_f32 v[86:87], v[86:87], v[100:101] op_sel_hi:[1,0]
	v_pk_mul_f32 v[84:85], v[84:85], v[100:101] op_sel_hi:[1,0]
	v_max_f32_e32 v92, 0, v92
	v_max_f32_e32 v88, 0, v88
	v_max_f32_e32 v93, 0, v93
	v_max_f32_e32 v89, 0, v89
	v_max_f32_e32 v94, 0, v94
	v_max_f32_e32 v90, 0, v90
	v_max_f32_e32 v95, 0, v95
	v_max_f32_e32 v91, 0, v91
	v_max_f32_e32 v80, 0, v80
	v_max_f32_e32 v81, 0, v81
	v_max_f32_e32 v82, 0, v82
	v_max_f32_e32 v83, 0, v83
	v_max_f32_e32 v84, 0, v84
	v_max_f32_e32 v85, 0, v85
	v_max_f32_e32 v86, 0, v86
	v_max_f32_e32 v87, 0, v87
	v_mul_f32_e32 v92, v92, v92
	v_mul_f32_e32 v88, v88, v88
	v_mul_f32_e32 v93, v93, v93
	v_mul_f32_e32 v89, v89, v89
	v_mul_f32_e32 v94, v94, v94
	v_mul_f32_e32 v90, v90, v90
	v_mul_f32_e32 v95, v95, v95
	v_mul_f32_e32 v91, v91, v91
	v_mul_f32_e32 v100, v80, v80
	v_mul_f32_e32 v101, v81, v81
	v_mul_f32_e32 v102, v82, v82
	v_mul_f32_e32 v103, v83, v83
	v_cvt_pk_bf16_f32 v80, v92, v93
	v_cvt_pk_bf16_f32 v81, v94, v95
	v_cvt_pk_bf16_f32 v82, v88, v89
	v_cvt_pk_bf16_f32 v83, v90, v91
	v_mul_f32_e32 v84, v84, v84
	v_mul_f32_e32 v85, v85, v85
	v_mul_f32_e32 v86, v86, v86
	v_mul_f32_e32 v87, v87, v87
	global_store_dwordx4 v[98:99], v[80:83], off
	s_nop 1
	v_cvt_pk_bf16_f32 v80, v84, v85
	v_cvt_pk_bf16_f32 v81, v86, v87
	v_cvt_pk_bf16_f32 v82, v100, v101
	v_cvt_pk_bf16_f32 v83, v102, v103
	global_store_dwordx4 v[98:99], v[80:83], off offset:256
	s_nop 0
	v_add_u32_e32 v96, 0x80, v146
	v_ashrrev_i32_e32 v97, 31, v96
	v_lshlrev_b64 v[98:99], 13, v[112:113]
	s_waitcnt vmcnt(10)
	v_add_f32_e32 v84, v188, v189
	v_add_f32_e32 v85, v190, v191
	v_add_f32_e32 v84, v84, v85
	ds_swizzle_b32 v85, v84 offset:swizzle(SWAP,16)
	s_waitcnt lgkmcnt(0)
	v_add_f32_e32 v84, v84, v85
	v_mov_b32_e32 v85, v84
	s_nop 1
	v_permlane32_swap_b32_e32 v84, v85
	v_add_f32_e32 v92, v84, v85
	s_nop 0
	v_lshl_add_u64 v[82:83], v[144:145], 0, v[98:99]
	v_mov_b32_e32 v80, v92
	v_fmamk_f32 v80, v80, 0x3a800000, v154
	v_mul_f32_e32 v81, 0x4b800000, v80
	v_cmp_gt_f32_e32 vcc, s48, v80
	s_nop 1
	v_cndmask_b32_e32 v80, v80, v81, vcc
	v_rsq_f32_e32 v84, v80
	v_lshlrev_b64 v[80:81], 6, v[96:97]
	v_lshl_add_u64 v[80:81], s[10:11], 0, v[80:81]
	v_mul_f32_e32 v85, 0x45800000, v84
	v_cndmask_b32_e32 v84, v84, v85, vcc
	v_pk_mul_f32 v[78:79], v[78:79], v[84:85] op_sel_hi:[1,0]
	v_pk_mul_f32 v[76:77], v[76:77], v[84:85] op_sel_hi:[1,0]
	v_pk_mul_f32 v[74:75], v[74:75], v[84:85] op_sel_hi:[1,0]
	v_pk_mul_f32 v[72:73], v[72:73], v[84:85] op_sel_hi:[1,0]
	v_pk_mul_f32 v[66:67], v[66:67], v[84:85] op_sel_hi:[1,0]
	v_pk_mul_f32 v[64:65], v[64:65], v[84:85] op_sel_hi:[1,0]
	v_pk_mul_f32 v[70:71], v[70:71], v[84:85] op_sel_hi:[1,0]
	v_pk_mul_f32 v[68:69], v[68:69], v[84:85] op_sel_hi:[1,0]
	v_max_f32_e32 v76, 0, v76
	v_max_f32_e32 v72, 0, v72
	v_max_f32_e32 v77, 0, v77
	v_max_f32_e32 v73, 0, v73
	v_max_f32_e32 v78, 0, v78
	v_max_f32_e32 v74, 0, v74
	v_max_f32_e32 v79, 0, v79
	v_max_f32_e32 v75, 0, v75
	v_max_f32_e32 v64, 0, v64
	v_max_f32_e32 v65, 0, v65
	v_max_f32_e32 v66, 0, v66
	v_max_f32_e32 v67, 0, v67
	v_max_f32_e32 v68, 0, v68
	v_max_f32_e32 v69, 0, v69
	v_max_f32_e32 v70, 0, v70
	v_max_f32_e32 v71, 0, v71
	v_mul_f32_e32 v76, v76, v76
	v_mul_f32_e32 v72, v72, v72
	v_mul_f32_e32 v77, v77, v77
	v_mul_f32_e32 v73, v73, v73
	v_mul_f32_e32 v78, v78, v78
	v_mul_f32_e32 v74, v74, v74
	v_mul_f32_e32 v79, v79, v79
	v_mul_f32_e32 v75, v75, v75
	v_mul_f32_e32 v84, v64, v64
	v_mul_f32_e32 v85, v65, v65
	v_mul_f32_e32 v86, v66, v66
	v_mul_f32_e32 v87, v67, v67
	v_cvt_pk_bf16_f32 v64, v76, v77
	v_cvt_pk_bf16_f32 v65, v78, v79
	v_cvt_pk_bf16_f32 v66, v72, v73
	v_cvt_pk_bf16_f32 v67, v74, v75
	v_mul_f32_e32 v68, v68, v68
	v_mul_f32_e32 v69, v69, v69
	v_mul_f32_e32 v70, v70, v70
	v_mul_f32_e32 v71, v71, v71
	global_store_dwordx4 v[82:83], v[64:67], off
	s_nop 1
	v_cvt_pk_bf16_f32 v64, v68, v69
	v_cvt_pk_bf16_f32 v65, v70, v71
	v_cvt_pk_bf16_f32 v66, v84, v85
	v_cvt_pk_bf16_f32 v67, v86, v87
	global_store_dwordx4 v[82:83], v[64:67], off offset:256
	s_nop 0
	v_add_u32_e32 v80, 0x90, v146
	v_ashrrev_i32_e32 v81, 31, v80
	v_lshlrev_b64 v[82:83], 13, v[96:97]
	s_waitcnt vmcnt(11)
	v_add_f32_e32 v68, v192, v193
	v_add_f32_e32 v69, v194, v195
	v_add_f32_e32 v68, v68, v69
	ds_swizzle_b32 v69, v68 offset:swizzle(SWAP,16)
	s_waitcnt lgkmcnt(0)
	v_add_f32_e32 v68, v68, v69
	v_mov_b32_e32 v69, v68
	s_nop 1
	v_permlane32_swap_b32_e32 v68, v69
	v_add_f32_e32 v76, v68, v69
	s_nop 0
	v_lshl_add_u64 v[66:67], v[144:145], 0, v[82:83]
	v_mov_b32_e32 v64, v76
	v_fmamk_f32 v64, v64, 0x3a800000, v154
	v_mul_f32_e32 v65, 0x4b800000, v64
	v_cmp_gt_f32_e32 vcc, s48, v64
	s_nop 1
	v_cndmask_b32_e32 v64, v64, v65, vcc
	v_rsq_f32_e32 v68, v64
	v_lshlrev_b64 v[64:65], 6, v[80:81]
	v_lshl_add_u64 v[64:65], s[10:11], 0, v[64:65]
	v_mul_f32_e32 v69, 0x45800000, v68
	v_cndmask_b32_e32 v68, v68, v69, vcc
	v_pk_mul_f32 v[62:63], v[62:63], v[68:69] op_sel_hi:[1,0]
	v_pk_mul_f32 v[60:61], v[60:61], v[68:69] op_sel_hi:[1,0]
	v_pk_mul_f32 v[58:59], v[58:59], v[68:69] op_sel_hi:[1,0]
	v_pk_mul_f32 v[56:57], v[56:57], v[68:69] op_sel_hi:[1,0]
	v_pk_mul_f32 v[50:51], v[50:51], v[68:69] op_sel_hi:[1,0]
	v_pk_mul_f32 v[48:49], v[48:49], v[68:69] op_sel_hi:[1,0]
	v_pk_mul_f32 v[54:55], v[54:55], v[68:69] op_sel_hi:[1,0]
	v_pk_mul_f32 v[52:53], v[52:53], v[68:69] op_sel_hi:[1,0]
	v_max_f32_e32 v60, 0, v60
	v_max_f32_e32 v56, 0, v56
	v_max_f32_e32 v61, 0, v61
	v_max_f32_e32 v57, 0, v57
	v_max_f32_e32 v62, 0, v62
	v_max_f32_e32 v58, 0, v58
	v_max_f32_e32 v63, 0, v63
	v_max_f32_e32 v59, 0, v59
	v_max_f32_e32 v48, 0, v48
	v_max_f32_e32 v49, 0, v49
	v_max_f32_e32 v50, 0, v50
	v_max_f32_e32 v51, 0, v51
	v_max_f32_e32 v52, 0, v52
	v_max_f32_e32 v53, 0, v53
	v_max_f32_e32 v54, 0, v54
	v_max_f32_e32 v55, 0, v55
	v_mul_f32_e32 v60, v60, v60
	v_mul_f32_e32 v56, v56, v56
	v_mul_f32_e32 v61, v61, v61
	v_mul_f32_e32 v57, v57, v57
	v_mul_f32_e32 v62, v62, v62
	v_mul_f32_e32 v58, v58, v58
	v_mul_f32_e32 v63, v63, v63
	v_mul_f32_e32 v59, v59, v59
	v_mul_f32_e32 v68, v48, v48
	v_mul_f32_e32 v69, v49, v49
	v_mul_f32_e32 v70, v50, v50
	v_mul_f32_e32 v71, v51, v51
	v_cvt_pk_bf16_f32 v48, v60, v61
	v_cvt_pk_bf16_f32 v49, v62, v63
	v_cvt_pk_bf16_f32 v50, v56, v57
	v_cvt_pk_bf16_f32 v51, v58, v59
	v_mul_f32_e32 v52, v52, v52
	v_mul_f32_e32 v53, v53, v53
	v_mul_f32_e32 v54, v54, v54
	v_mul_f32_e32 v55, v55, v55
	global_store_dwordx4 v[66:67], v[48:51], off
	s_nop 1
	v_cvt_pk_bf16_f32 v48, v52, v53
	v_cvt_pk_bf16_f32 v49, v54, v55
	v_cvt_pk_bf16_f32 v50, v68, v69
	v_cvt_pk_bf16_f32 v51, v70, v71
	global_store_dwordx4 v[66:67], v[48:51], off offset:256
	s_nop 0
	v_add_u32_e32 v64, 0xa0, v146
	v_ashrrev_i32_e32 v65, 31, v64
	v_lshlrev_b64 v[66:67], 13, v[80:81]
	s_waitcnt vmcnt(12)
	v_add_f32_e32 v52, v196, v197
	v_add_f32_e32 v53, v198, v199
	v_add_f32_e32 v52, v52, v53
	ds_swizzle_b32 v53, v52 offset:swizzle(SWAP,16)
	s_waitcnt lgkmcnt(0)
	v_add_f32_e32 v52, v52, v53
	v_mov_b32_e32 v53, v52
	s_nop 1
	v_permlane32_swap_b32_e32 v52, v53
	v_add_f32_e32 v60, v52, v53
	s_nop 0
	v_lshl_add_u64 v[50:51], v[144:145], 0, v[66:67]
	v_mov_b32_e32 v48, v60
	v_fmamk_f32 v48, v48, 0x3a800000, v154
	v_mul_f32_e32 v49, 0x4b800000, v48
	v_cmp_gt_f32_e32 vcc, s48, v48
	s_nop 1
	v_cndmask_b32_e32 v48, v48, v49, vcc
	v_rsq_f32_e32 v52, v48
	v_lshlrev_b64 v[48:49], 6, v[64:65]
	v_lshl_add_u64 v[48:49], s[10:11], 0, v[48:49]
	v_mul_f32_e32 v53, 0x45800000, v52
	v_cndmask_b32_e32 v52, v52, v53, vcc
	v_pk_mul_f32 v[46:47], v[46:47], v[52:53] op_sel_hi:[1,0]
	v_pk_mul_f32 v[44:45], v[44:45], v[52:53] op_sel_hi:[1,0]
	v_pk_mul_f32 v[42:43], v[42:43], v[52:53] op_sel_hi:[1,0]
	v_pk_mul_f32 v[40:41], v[40:41], v[52:53] op_sel_hi:[1,0]
	v_pk_mul_f32 v[34:35], v[34:35], v[52:53] op_sel_hi:[1,0]
	v_pk_mul_f32 v[32:33], v[32:33], v[52:53] op_sel_hi:[1,0]
	v_pk_mul_f32 v[38:39], v[38:39], v[52:53] op_sel_hi:[1,0]
	v_pk_mul_f32 v[36:37], v[36:37], v[52:53] op_sel_hi:[1,0]
	v_max_f32_e32 v44, 0, v44
	v_max_f32_e32 v40, 0, v40
	v_max_f32_e32 v45, 0, v45
	v_max_f32_e32 v41, 0, v41
	v_max_f32_e32 v46, 0, v46
	v_max_f32_e32 v42, 0, v42
	v_max_f32_e32 v47, 0, v47
	v_max_f32_e32 v43, 0, v43
	v_max_f32_e32 v32, 0, v32
	v_max_f32_e32 v33, 0, v33
	v_max_f32_e32 v34, 0, v34
	v_max_f32_e32 v35, 0, v35
	v_max_f32_e32 v36, 0, v36
	v_max_f32_e32 v37, 0, v37
	v_max_f32_e32 v38, 0, v38
	v_max_f32_e32 v39, 0, v39
	v_mul_f32_e32 v44, v44, v44
	v_mul_f32_e32 v40, v40, v40
	v_mul_f32_e32 v45, v45, v45
	v_mul_f32_e32 v41, v41, v41
	v_mul_f32_e32 v46, v46, v46
	v_mul_f32_e32 v42, v42, v42
	v_mul_f32_e32 v47, v47, v47
	v_mul_f32_e32 v43, v43, v43
	v_mul_f32_e32 v52, v32, v32
	v_mul_f32_e32 v53, v33, v33
	v_mul_f32_e32 v54, v34, v34
	v_mul_f32_e32 v55, v35, v35
	v_cvt_pk_bf16_f32 v32, v44, v45
	v_cvt_pk_bf16_f32 v33, v46, v47
	v_cvt_pk_bf16_f32 v34, v40, v41
	v_cvt_pk_bf16_f32 v35, v42, v43
	v_mul_f32_e32 v36, v36, v36
	v_mul_f32_e32 v37, v37, v37
	v_mul_f32_e32 v38, v38, v38
	v_mul_f32_e32 v39, v39, v39
	global_store_dwordx4 v[50:51], v[32:35], off
	s_nop 1
	v_cvt_pk_bf16_f32 v32, v36, v37
	v_cvt_pk_bf16_f32 v33, v38, v39
	v_cvt_pk_bf16_f32 v34, v52, v53
	v_cvt_pk_bf16_f32 v35, v54, v55
	global_store_dwordx4 v[50:51], v[32:35], off offset:256
	s_nop 0
	v_add_u32_e32 v48, 0xb0, v146
	v_ashrrev_i32_e32 v49, 31, v48
	v_lshlrev_b64 v[50:51], 13, v[64:65]
	s_waitcnt vmcnt(13)
	v_add_f32_e32 v36, v200, v201
	v_add_f32_e32 v37, v202, v203
	v_add_f32_e32 v36, v36, v37
	ds_swizzle_b32 v37, v36 offset:swizzle(SWAP,16)
	s_waitcnt lgkmcnt(0)
	v_add_f32_e32 v36, v36, v37
	v_mov_b32_e32 v37, v36
	s_nop 1
	v_permlane32_swap_b32_e32 v36, v37
	v_add_f32_e32 v44, v36, v37
	s_nop 0
	v_lshl_add_u64 v[34:35], v[144:145], 0, v[50:51]
	v_mov_b32_e32 v32, v44
	v_fmamk_f32 v32, v32, 0x3a800000, v154
	v_mul_f32_e32 v33, 0x4b800000, v32
	v_cmp_gt_f32_e32 vcc, s48, v32
	s_nop 1
	v_cndmask_b32_e32 v32, v32, v33, vcc
	v_rsq_f32_e32 v36, v32
	v_lshlrev_b64 v[32:33], 6, v[48:49]
	v_lshl_add_u64 v[32:33], s[10:11], 0, v[32:33]
	v_mul_f32_e32 v37, 0x45800000, v36
	v_cndmask_b32_e32 v36, v36, v37, vcc
	v_pk_mul_f32 v[30:31], v[30:31], v[36:37] op_sel_hi:[1,0]
	v_pk_mul_f32 v[28:29], v[28:29], v[36:37] op_sel_hi:[1,0]
	v_pk_mul_f32 v[26:27], v[26:27], v[36:37] op_sel_hi:[1,0]
	v_pk_mul_f32 v[24:25], v[24:25], v[36:37] op_sel_hi:[1,0]
	v_pk_mul_f32 v[18:19], v[18:19], v[36:37] op_sel_hi:[1,0]
	v_pk_mul_f32 v[16:17], v[16:17], v[36:37] op_sel_hi:[1,0]
	v_pk_mul_f32 v[22:23], v[22:23], v[36:37] op_sel_hi:[1,0]
	v_pk_mul_f32 v[20:21], v[20:21], v[36:37] op_sel_hi:[1,0]
	v_max_f32_e32 v28, 0, v28
	v_max_f32_e32 v24, 0, v24
	v_max_f32_e32 v29, 0, v29
	v_max_f32_e32 v25, 0, v25
	v_max_f32_e32 v30, 0, v30
	v_max_f32_e32 v26, 0, v26
	v_max_f32_e32 v31, 0, v31
	v_max_f32_e32 v27, 0, v27
	v_max_f32_e32 v16, 0, v16
	v_max_f32_e32 v17, 0, v17
	v_max_f32_e32 v18, 0, v18
	v_max_f32_e32 v19, 0, v19
	v_max_f32_e32 v20, 0, v20
	v_max_f32_e32 v21, 0, v21
	v_max_f32_e32 v22, 0, v22
	v_max_f32_e32 v23, 0, v23
	v_mul_f32_e32 v28, v28, v28
	v_mul_f32_e32 v24, v24, v24
	v_mul_f32_e32 v29, v29, v29
	v_mul_f32_e32 v25, v25, v25
	v_mul_f32_e32 v30, v30, v30
	v_mul_f32_e32 v26, v26, v26
	v_mul_f32_e32 v31, v31, v31
	v_mul_f32_e32 v27, v27, v27
	v_mul_f32_e32 v36, v16, v16
	v_mul_f32_e32 v37, v17, v17
	v_mul_f32_e32 v38, v18, v18
	v_mul_f32_e32 v39, v19, v19
	v_cvt_pk_bf16_f32 v16, v28, v29
	v_cvt_pk_bf16_f32 v17, v30, v31
	v_cvt_pk_bf16_f32 v18, v24, v25
	v_cvt_pk_bf16_f32 v19, v26, v27
	v_mul_f32_e32 v20, v20, v20
	v_mul_f32_e32 v21, v21, v21
	v_mul_f32_e32 v22, v22, v22
	v_mul_f32_e32 v23, v23, v23
	global_store_dwordx4 v[34:35], v[16:19], off
	s_andn2_b64 vcc, exec, s[4:5]
	s_mov_b64 s[4:5], -1
	v_cvt_pk_bf16_f32 v16, v20, v21
	v_cvt_pk_bf16_f32 v17, v22, v23
	v_cvt_pk_bf16_f32 v18, v36, v37
	v_cvt_pk_bf16_f32 v19, v38, v39
	global_store_dwordx4 v[34:35], v[16:19], off offset:256
	s_nop 0
	s_waitcnt vmcnt(14)
	v_add_f32_e32 v20, v208, v209
	v_add_f32_e32 v21, v210, v211
	v_add_f32_e32 v20, v20, v21
	ds_swizzle_b32 v21, v20 offset:swizzle(SWAP,16)
	s_waitcnt lgkmcnt(0)
	v_add_f32_e32 v20, v20, v21
	v_mov_b32_e32 v21, v20
	s_nop 1
	v_permlane32_swap_b32_e32 v20, v21
	v_add_f32_e32 v28, v20, v21
	s_nop 0
	s_nop 0
	v_mov_b32_e32 v16, v28
	v_fmamk_f32 v16, v16, 0x3a800000, v154
	v_mul_f32_e32 v17, 0x4b800000, v16
	v_cmp_gt_f32_e64 s[6:7], s48, v16
	s_nop 1
	v_cndmask_b32_e64 v16, v16, v17, s[6:7]
	v_rsq_f32_e32 v18, v16
	v_lshlrev_b64 v[16:17], 13, v[48:49]
	v_lshl_add_u64 v[16:17], v[144:145], 0, v[16:17]
	v_mul_f32_e32 v19, 0x45800000, v18
	v_cndmask_b32_e64 v18, v18, v19, s[6:7]
	v_pk_mul_f32 v[14:15], v[14:15], v[18:19] op_sel_hi:[1,0]
	v_pk_mul_f32 v[12:13], v[12:13], v[18:19] op_sel_hi:[1,0]
	v_pk_mul_f32 v[10:11], v[10:11], v[18:19] op_sel_hi:[1,0]
	v_pk_mul_f32 v[8:9], v[8:9], v[18:19] op_sel_hi:[1,0]
	v_pk_mul_f32 v[2:3], v[2:3], v[18:19] op_sel_hi:[1,0]
	v_pk_mul_f32 v[0:1], v[0:1], v[18:19] op_sel_hi:[1,0]
	v_pk_mul_f32 v[6:7], v[6:7], v[18:19] op_sel_hi:[1,0]
	v_pk_mul_f32 v[4:5], v[4:5], v[18:19] op_sel_hi:[1,0]
	v_max_f32_e32 v12, 0, v12
	v_max_f32_e32 v8, 0, v8
	v_max_f32_e32 v13, 0, v13
	v_max_f32_e32 v9, 0, v9
	v_max_f32_e32 v14, 0, v14
	v_max_f32_e32 v10, 0, v10
	v_max_f32_e32 v15, 0, v15
	v_max_f32_e32 v11, 0, v11
	v_max_f32_e32 v0, 0, v0
	v_max_f32_e32 v1, 0, v1
	v_max_f32_e32 v2, 0, v2
	v_max_f32_e32 v3, 0, v3
	v_max_f32_e32 v4, 0, v4
	v_max_f32_e32 v5, 0, v5
	v_max_f32_e32 v6, 0, v6
	v_max_f32_e32 v7, 0, v7
	v_mul_f32_e32 v12, v12, v12
	v_mul_f32_e32 v8, v8, v8
	v_mul_f32_e32 v13, v13, v13
	v_mul_f32_e32 v9, v9, v9
	v_mul_f32_e32 v14, v14, v14
	v_mul_f32_e32 v10, v10, v10
	v_mul_f32_e32 v15, v15, v15
	v_mul_f32_e32 v11, v11, v11
	v_mul_f32_e32 v18, v0, v0
	v_mul_f32_e32 v19, v1, v1
	v_mul_f32_e32 v20, v2, v2
	v_mul_f32_e32 v21, v3, v3
	v_cvt_pk_bf16_f32 v0, v12, v13
	v_cvt_pk_bf16_f32 v1, v14, v15
	v_cvt_pk_bf16_f32 v2, v8, v9
	v_cvt_pk_bf16_f32 v3, v10, v11
	v_mul_f32_e32 v4, v4, v4
	v_mul_f32_e32 v5, v5, v5
	v_mul_f32_e32 v6, v6, v6
	v_mul_f32_e32 v7, v7, v7
	global_store_dwordx4 v[16:17], v[0:3], off
	s_nop 1
	v_cvt_pk_bf16_f32 v0, v4, v5
	v_cvt_pk_bf16_f32 v1, v6, v7
	v_cvt_pk_bf16_f32 v2, v18, v19
	v_cvt_pk_bf16_f32 v3, v20, v21
	global_store_dwordx4 v[16:17], v[0:3], off offset:256
	s_cbranch_vccnz .LBB0_2837
	s_andn2_b64 vcc, exec, s[2:3]
	s_cbranch_vccnz .LBB0_2836
	s_barrier
	s_branch .LBB0_2836
